# P4 epilogue stores with the nt (streaming) hint
# baseline (speedup 1.0000x reference)
.LBB0_1053:
	s_lshl_b32 s0, s50, 8
	s_add_i32 s0, s78, s0
	s_and_b32 s0, s0, 0x7fffff80
	s_lshl_b32 s0, s0, 1
	s_add_u32 s58, s79, s0
	s_addc_u32 s59, s82, 0
	s_lshl_b32 s0, s50, 2
	s_or_b32 s0, s0, s74
	s_mulk_i32 s0, 0x60
	s_ashr_i32 s1, s0, 31
	s_lshl_b64 s[0:1], s[0:1], 1
	s_add_u32 s54, s10, s0
	s_addc_u32 s55, s11, s1
	s_and_b64 s[0:1], s[8:9], exec
	s_cselect_b32 s0, s87, 0x340000
	s_add_u32 s50, s38, s0
	s_addc_u32 s51, s39, 0
	v_lshl_add_u64 v[4:5], v[200:201], 4, s[50:51]
	global_load_dwordx4 v[164:167], v[4:5], off
	global_load_dwordx4 v[236:239], v[4:5], off offset:2048
	global_load_dwordx4 v[240:243], v[4:5], off offset:2304
	global_load_dwordx4 v[244:247], v[4:5], off offset:2560
	global_load_dwordx4 v[248:251], v[4:5], off offset:2816
	v_add_u32_e32 v206, 16, v200
	v_add_u32_e32 v204, 32, v200
	v_add_u32_e32 v202, 48, v200
	v_ashrrev_i32_e32 v207, 31, v206
	v_ashrrev_i32_e32 v205, 31, v204
	v_ashrrev_i32_e32 v203, 31, v202
	v_lshl_add_u64 v[4:5], v[206:207], 4, s[50:51]
	v_lshl_add_u64 v[122:123], v[204:205], 4, s[50:51]
	v_lshl_add_u64 v[124:125], v[202:203], 4, s[50:51]
	global_load_dwordx4 v[178:181], v[4:5], off
	global_load_dwordx4 v[142:145], v[122:123], off
	s_nop 0
	global_load_dwordx4 v[122:125], v[124:125], off
	v_cndmask_b32_e64 v3, v218, v219, s[8:9]
	v_lshlrev_b64 v[210:211], 1, v[162:163]
	v_lshl_add_u64 v[198:199], v[8:9], 3, s[22:23]
	s_mov_b64 s[8:9], -1
	s_and_b64 vcc, exec, s[52:53]
	s_waitcnt vmcnt(0)
	v_mov_b32_e32 v4, v165
	v_mov_b32_e32 v5, v166
	v_mov_b32_e32 v165, v167
	v_pk_add_f32 v[4:5], v[4:5], v[164:165]
	s_nop 0
	v_add_f32_e32 v4, v4, v5
	v_fmaak_f32 v4, v3, v4, 0x358637bd
	v_rsq_f32_e32 v220, v4
	v_lshl_add_u64 v[4:5], s[58:59], 0, v[210:211]
	v_pk_mul_f32 v[160:161], v[160:161], v[220:221] op_sel_hi:[1,0]
	v_pk_mul_f32 v[208:209], v[158:159], v[220:221] op_sel_hi:[1,0]
	v_pk_mul_f32 v[156:157], v[156:157], v[220:221] op_sel_hi:[1,0]
	v_pk_mul_f32 v[158:159], v[154:155], v[220:221] op_sel_hi:[1,0]
	v_pk_mul_f32 v[152:153], v[152:153], v[220:221] op_sel_hi:[1,0]
	v_pk_mul_f32 v[154:155], v[150:151], v[220:221] op_sel_hi:[1,0]
	v_pk_mul_f32 v[148:149], v[148:149], v[220:221] op_sel_hi:[1,0]
	v_pk_mul_f32 v[150:151], v[146:147], v[220:221] op_sel_hi:[1,0]
	s_cbranch_vccz .LBB0_1063
	s_and_b64 vcc, exec, s[56:57]
	s_cbranch_vccz .LBB0_1060
	v_lshlrev_b64 v[146:147], 11, v[200:201]
	v_lshl_add_u64 v[146:147], v[4:5], 0, v[146:147]
	s_and_b64 vcc, exec, s[26:27]
	s_cbranch_vccz .LBB0_1057
	v_cvt_pk_bf16_f32 v162, v208, v209
	v_cvt_pk_bf16_f32 v163, v160, v161
	v_cvt_pk_bf16_f32 v164, v158, v159
	v_cvt_pk_bf16_f32 v165, v156, v157
	global_store_dwordx4 v[146:147], v[162:165], off nt
	s_mov_b64 s[8:9], 0
	s_nop 0
	v_cvt_pk_bf16_f32 v162, v154, v155
	v_cvt_pk_bf16_f32 v163, v152, v153
	v_cvt_pk_bf16_f32 v164, v150, v151
	v_cvt_pk_bf16_f32 v165, v148, v149
	global_store_dwordx4 v[146:147], v[162:165], off offset:64 nt
.LBB0_1057:
	s_andn2_b64 vcc, exec, s[8:9]
	s_cbranch_vccnz .LBB0_1059
	v_mul_f32_e32 v7, v209, v209
	v_mul_f32_e32 v162, v161, v161
	v_fmac_f32_e32 v7, v208, v208
	v_fmac_f32_e32 v162, v160, v160
	v_add_f32_e32 v7, v7, v162
	v_mul_f32_e32 v162, v159, v159
	v_mul_f32_e32 v163, v157, v157
	v_fmac_f32_e32 v162, v158, v158
	v_fmac_f32_e32 v163, v156, v156
	v_add_f32_e32 v162, v162, v163
	v_add_f32_e32 v7, v7, v162
	v_mul_f32_e32 v162, v155, v155
	v_mul_f32_e32 v163, v153, v153
	v_fmac_f32_e32 v162, v154, v154
	v_fmac_f32_e32 v163, v152, v152
	v_add_f32_e32 v162, v162, v163
	v_mul_f32_e32 v163, v151, v151
	v_mul_f32_e32 v164, v149, v149
	v_fmac_f32_e32 v163, v150, v150
	v_fmac_f32_e32 v164, v148, v148
	v_add_f32_e32 v163, v163, v164
	v_add_f32_e32 v162, v162, v163
	v_add_f32_e32 v7, v7, v162
	v_mov_b32_e32 v162, v7
	s_nop 1
	v_permlane16_swap_b32_e32 v7, v162
	v_add_f32_e32 v7, v7, v162
	v_mov_b32_e32 v162, v7
	s_nop 1
	v_permlane32_swap_b32_e32 v7, v162
	v_add_f32_e32 v7, v7, v162
	v_fmamk_f32 v7, v7, 0x3c800000, v217
	v_rsq_f32_e32 v7, v7
	v_pk_mul_f32 v[162:163], v[38:39], v[208:209]
	v_pk_mul_f32 v[164:165], v[40:41], v[160:161]
	v_pk_mul_f32 v[168:169], v[34:35], v[158:159]
	v_mul_f32_e32 v162, v162, v7
	v_mul_f32_e32 v163, v163, v7
	v_cvt_pk_bf16_f32 v162, v162, v163
	v_mul_f32_e32 v163, v164, v7
	v_mul_f32_e32 v164, v165, v7
	v_pk_mul_f32 v[166:167], v[36:37], v[156:157]
	v_cvt_pk_bf16_f32 v163, v163, v164
	v_mul_f32_e32 v164, v168, v7
	v_mul_f32_e32 v165, v169, v7
	v_cvt_pk_bf16_f32 v164, v164, v165
	v_mul_f32_e32 v165, v166, v7
	v_mul_f32_e32 v166, v167, v7
	v_cvt_pk_bf16_f32 v165, v165, v166
	global_store_dwordx4 v[146:147], v[162:165], off nt
	v_pk_mul_f32 v[168:169], v[26:27], v[150:151]
	v_pk_mul_f32 v[166:167], v[28:29], v[148:149]
	v_pk_mul_f32 v[162:163], v[30:31], v[154:155]
	v_pk_mul_f32 v[164:165], v[32:33], v[152:153]
	v_mul_f32_e32 v162, v162, v7
	v_mul_f32_e32 v163, v163, v7
	v_cvt_pk_bf16_f32 v162, v162, v163
	v_mul_f32_e32 v163, v164, v7
	v_mul_f32_e32 v164, v165, v7
	v_cvt_pk_bf16_f32 v163, v163, v164
	v_mul_f32_e32 v164, v168, v7
	v_mul_f32_e32 v165, v169, v7
	v_cvt_pk_bf16_f32 v164, v164, v165
	v_mul_f32_e32 v165, v166, v7
	v_mul_f32_e32 v7, v167, v7
	v_cvt_pk_bf16_f32 v165, v165, v7
	global_store_dwordx4 v[146:147], v[162:165], off offset:64 nt

.LBB0_1060:
	s_nop 0
	v_mov_b64_e32 v[162:163], v[174:175]
	v_mov_b64_e32 v[166:167], v[170:171]
	s_andn2_b64 vcc, exec, s[8:9]
	v_mov_b64_e32 v[164:165], v[176:177]
	v_mov_b64_e32 v[168:169], v[172:173]
	s_cbranch_vccnz .LBB0_1062
	v_ashrrev_i32_e32 v7, 31, v206
	v_lshrrev_b32_e32 v7, 19, v7
	v_add_u32_e32 v7, v206, v7
	v_and_b32_e32 v7, 0xffffe000, v7
	v_sub_u32_e32 v146, v206, v7
	v_ashrrev_i32_e32 v147, 31, v146
	v_lshlrev_b64 v[146:147], 7, v[146:147]
	v_lshl_add_u64 v[146:147], v[198:199], 0, v[146:147]
	global_load_dwordx4 v[166:169], v[146:147], off offset:16
	global_load_dwordx4 v[162:165], v[146:147], off
	v_mul_f32_e32 v7, v209, v209
	v_mul_f32_e32 v146, v161, v161
	v_fmac_f32_e32 v7, v208, v208
	v_fmac_f32_e32 v146, v160, v160
	v_add_f32_e32 v7, v7, v146
	v_mul_f32_e32 v146, v159, v159
	v_mul_f32_e32 v147, v157, v157
	v_fmac_f32_e32 v146, v158, v158
	v_fmac_f32_e32 v147, v156, v156
	v_add_f32_e32 v146, v146, v147
	v_add_f32_e32 v7, v7, v146
	v_mov_b32_e32 v146, v7
	s_nop 1
	v_permlane16_swap_b32_e32 v7, v146
	v_add_f32_e32 v7, v7, v146
	v_mov_b32_e32 v146, v7
	s_nop 1
	v_permlane32_swap_b32_e32 v7, v146
	v_add_f32_e32 v7, v7, v146
	v_fmamk_f32 v7, v7, 0x3d000000, v217
	v_rsq_f32_e32 v146, v7
	v_mov_b32_e32 v220, v208
	v_mov_b32_e32 v221, v158
	v_mov_b32_e32 v222, v38
	v_pk_mul_f32 v[220:221], v[220:221], v[146:147] op_sel_hi:[1,0]
	v_mov_b32_e32 v223, v34
	v_pk_mul_f32 v[220:221], v[222:223], v[220:221]
	s_nop 0
	v_pk_mul_f32 v[224:225], v[174:175], v[220:221]
	v_pk_mul_f32 v[220:221], v[174:175], v[220:221] op_sel:[1,0] op_sel_hi:[0,1]
	v_add_f32_e32 v147, v220, v221
	v_mov_b32_e32 v220, v209
	v_mov_b32_e32 v221, v159
	v_sub_f32_e32 v7, v224, v225
	v_pk_mul_f32 v[220:221], v[220:221], v[146:147] op_sel_hi:[1,0]
	v_mov_b32_e32 v224, v39
	v_mov_b32_e32 v225, v35
	v_pk_mul_f32 v[220:221], v[224:225], v[220:221]
	v_mul_f32_e32 v201, 0x3e16c740, v147
	v_pk_mul_f32 v[226:227], v[176:177], v[220:221]
	v_pk_mul_f32 v[220:221], v[176:177], v[220:221] op_sel:[1,0] op_sel_hi:[0,1]
	v_sub_f32_e32 v147, v226, v227
	v_mul_f32_e32 v230, 0x3e16c740, v147
	v_add_f32_e32 v147, v220, v221
	v_mov_b32_e32 v220, v160
	v_mov_b32_e32 v221, v156
	v_pk_mul_f32 v[220:221], v[220:221], v[146:147] op_sel_hi:[1,0]
	v_mov_b32_e32 v226, v40
	v_mov_b32_e32 v227, v36
	v_pk_mul_f32 v[220:221], v[226:227], v[220:221]
	v_mul_f32_e32 v231, 0x3e16c740, v147
	v_pk_mul_f32 v[228:229], v[170:171], v[220:221]
	v_pk_mul_f32 v[220:221], v[170:171], v[220:221] op_sel:[1,0] op_sel_hi:[0,1]
	v_sub_f32_e32 v147, v228, v229
	v_mul_f32_e32 v232, 0x3e16c740, v147
	v_add_f32_e32 v147, v220, v221
	v_mov_b32_e32 v220, v161
	v_mov_b32_e32 v221, v157
	v_mul_f32_e32 v233, 0x3e16c740, v147
	v_pk_mul_f32 v[146:147], v[220:221], v[146:147] op_sel_hi:[1,0]
	v_mov_b32_e32 v220, v41
	v_mov_b32_e32 v221, v37
	v_pk_mul_f32 v[146:147], v[220:221], v[146:147]
	v_mul_f32_e32 v7, 0x3e16c740, v7
	v_pk_mul_f32 v[228:229], v[172:173], v[146:147]
	v_pk_mul_f32 v[146:147], v[172:173], v[146:147] op_sel:[1,0] op_sel_hi:[0,1]
	v_add_f32_e32 v146, v146, v147
	v_mul_f32_e32 v234, 0x3e16c740, v146
	v_mov_b64_e32 v[146:147], s[28:29]
	v_sub_f32_e32 v228, v228, v229
	v_mad_i64_i32 v[146:147], s[0:1], v200, s70, v[146:147]
	v_mul_f32_e32 v229, 0x3e16c740, v228
	v_cvt_pk_bf16_f32 v228, v7, v230
	v_lshl_add_u64 v[146:147], v[8:9], 1, v[146:147]
	v_cvt_pk_bf16_f32 v229, v232, v229
	global_store_dwordx2 v[146:147], v[228:229], off offset:128 nt
	v_cvt_pk_bf16_f32 v228, v201, v231
	v_mul_f32_e32 v7, v155, v155
	v_mul_f32_e32 v201, v153, v153
	v_fmac_f32_e32 v7, v154, v154
	v_fmac_f32_e32 v201, v152, v152
	v_add_f32_e32 v7, v7, v201
	v_mul_f32_e32 v201, v151, v151
	v_mul_f32_e32 v230, v149, v149
	v_fmac_f32_e32 v201, v150, v150
	v_fmac_f32_e32 v230, v148, v148
	v_add_f32_e32 v201, v201, v230
	v_add_f32_e32 v7, v7, v201
	v_mov_b32_e32 v201, v7
	s_nop 1
	v_permlane16_swap_b32_e32 v7, v201
	v_add_f32_e32 v7, v7, v201
	v_mov_b32_e32 v201, v7
	s_nop 1
	v_permlane32_swap_b32_e32 v7, v201
	v_add_f32_e32 v7, v7, v201
	v_fmamk_f32 v7, v7, 0x3d000000, v217
	v_rsq_f32_e32 v230, v7
	v_cvt_pk_bf16_f32 v229, v233, v234
	global_store_dwordx2 v[146:147], v[228:229], off offset:160 nt
	v_mov_b32_e32 v228, v154
	v_mov_b32_e32 v229, v150
	v_pk_mul_f32 v[228:229], v[228:229], v[230:231] op_sel_hi:[1,0]
	s_nop 0
	v_pk_mul_f32 v[222:223], v[222:223], v[228:229]
	s_nop 0
	v_pk_mul_f32 v[228:229], v[174:175], v[222:223]
	v_pk_mul_f32 v[222:223], v[174:175], v[222:223] op_sel:[1,0] op_sel_hi:[0,1]
	v_add_f32_e32 v201, v222, v223
	v_mov_b32_e32 v222, v155
	v_mov_b32_e32 v223, v151
	v_pk_mul_f32 v[222:223], v[222:223], v[230:231] op_sel_hi:[1,0]
	v_sub_f32_e32 v7, v228, v229
	v_pk_mul_f32 v[222:223], v[224:225], v[222:223]
	v_mul_f32_e32 v7, 0x3e16c740, v7
	v_pk_mul_f32 v[224:225], v[176:177], v[222:223]
	v_pk_mul_f32 v[222:223], v[176:177], v[222:223] op_sel:[1,0] op_sel_hi:[0,1]
	v_add_f32_e32 v222, v222, v223
	v_mul_f32_e32 v229, 0x3e16c740, v222
	v_mov_b32_e32 v222, v152
	v_mov_b32_e32 v223, v148
	v_pk_mul_f32 v[222:223], v[222:223], v[230:231] op_sel_hi:[1,0]
	v_sub_f32_e32 v224, v224, v225
	v_pk_mul_f32 v[222:223], v[226:227], v[222:223]
	v_mul_f32_e32 v228, 0x3e16c740, v224
	v_pk_mul_f32 v[224:225], v[170:171], v[222:223]
	v_pk_mul_f32 v[222:223], v[170:171], v[222:223] op_sel:[1,0] op_sel_hi:[0,1]
	v_add_f32_e32 v222, v222, v223
	v_sub_f32_e32 v224, v224, v225
	v_mul_f32_e32 v225, 0x3e16c740, v222
	v_mov_b32_e32 v222, v153
	v_mov_b32_e32 v223, v149
	v_pk_mul_f32 v[222:223], v[222:223], v[230:231] op_sel_hi:[1,0]
	v_mul_f32_e32 v224, 0x3e16c740, v224
	v_pk_mul_f32 v[220:221], v[220:221], v[222:223]
	v_mul_f32_e32 v201, 0x3e16c740, v201
	v_pk_mul_f32 v[222:223], v[172:173], v[220:221]
	v_pk_mul_f32 v[220:221], v[172:173], v[220:221] op_sel:[1,0] op_sel_hi:[0,1]
	v_sub_f32_e32 v222, v222, v223
	v_add_f32_e32 v220, v220, v221
	v_mul_f32_e32 v222, 0x3e16c740, v222
	v_mul_f32_e32 v223, 0x3e16c740, v220
	v_cvt_pk_bf16_f32 v220, v7, v228
	v_cvt_pk_bf16_f32 v221, v224, v222
	global_store_dwordx2 v[146:147], v[220:221], off offset:320 nt
	v_cvt_pk_bf16_f32 v220, v201, v229
	v_cvt_pk_bf16_f32 v221, v225, v223
	global_store_dwordx2 v[146:147], v[220:221], off offset:352 nt

.Lew4_0:
	v_mul_f32_e32 v162, v161, v161
	v_fmac_f32_e32 v7, v208, v208
	v_fmac_f32_e32 v162, v160, v160
	v_add_f32_e32 v7, v7, v162
	v_mul_f32_e32 v162, v159, v159
	v_mul_f32_e32 v163, v157, v157
	v_fmac_f32_e32 v162, v158, v158
	v_fmac_f32_e32 v163, v156, v156
	v_add_f32_e32 v162, v162, v163
	v_add_f32_e32 v7, v7, v162
	v_mul_f32_e32 v162, v155, v155
	v_mul_f32_e32 v163, v153, v153
	v_fmac_f32_e32 v162, v154, v154
	v_fmac_f32_e32 v163, v152, v152
	v_add_f32_e32 v162, v162, v163
	v_mul_f32_e32 v163, v151, v151
	v_mul_f32_e32 v164, v149, v149
	v_fmac_f32_e32 v163, v150, v150
	v_fmac_f32_e32 v164, v148, v148
	v_add_f32_e32 v163, v163, v164
	v_add_f32_e32 v162, v162, v163
	v_add_f32_e32 v7, v7, v162
	v_mov_b32_e32 v162, v7
	s_nop 1
	v_permlane16_swap_b32_e32 v7, v162
	v_add_f32_e32 v7, v7, v162
	v_mov_b32_e32 v162, v7
	s_nop 1
	v_permlane32_swap_b32_e32 v7, v162
	v_add_f32_e32 v7, v7, v162
	v_fmamk_f32 v7, v7, 0x3c800000, v217
	v_rsq_f32_e32 v7, v7
	v_pk_mul_f32 v[164:165], v[38:39], v[208:209]
	v_pk_mul_f32 v[160:161], v[40:41], v[160:161]
	v_pk_mul_f32 v[166:167], v[36:37], v[156:157]
	v_mul_f32_e32 v7, 0x3e16c740, v7
	v_pk_mul_f32 v[158:159], v[34:35], v[158:159]
	v_mul_f32_e32 v156, v164, v7
	v_mul_f32_e32 v157, v165, v7
	v_cvt_pk_bf16_f32 v156, v156, v157
	v_mul_f32_e32 v157, v160, v7
	v_mul_f32_e32 v158, v158, v7
	v_mul_f32_e32 v159, v159, v7
	v_mad_i64_i32 v[162:163], s[0:1], v200, s70, v[146:147]
	v_mul_f32_e32 v160, v161, v7
	v_cvt_pk_bf16_f32 v157, v157, v160
	v_cvt_pk_bf16_f32 v158, v158, v159
	v_mul_f32_e32 v159, v166, v7
	v_pk_mul_f32 v[154:155], v[30:31], v[154:155]
	v_mul_f32_e32 v160, v167, v7
	v_cvt_pk_bf16_f32 v159, v159, v160
	global_store_dwordx4 v[162:163], v[156:159], off nt
	v_pk_mul_f32 v[152:153], v[32:33], v[152:153]
	v_pk_mul_f32 v[150:151], v[26:27], v[150:151]
	v_pk_mul_f32 v[156:157], v[28:29], v[148:149]
	v_mul_f32_e32 v148, v154, v7
	v_mul_f32_e32 v149, v155, v7
	v_cvt_pk_bf16_f32 v148, v148, v149
	v_mul_f32_e32 v149, v152, v7
	v_mul_f32_e32 v150, v150, v7
	v_mul_f32_e32 v151, v151, v7
	v_mul_f32_e32 v152, v153, v7
	v_cvt_pk_bf16_f32 v149, v149, v152
	v_cvt_pk_bf16_f32 v150, v150, v151
	v_mul_f32_e32 v151, v156, v7
	v_mul_f32_e32 v7, v157, v7
	v_cvt_pk_bf16_f32 v151, v151, v7
	global_store_dwordx4 v[162:163], v[148:151], off offset:64 nt
	v_mov_b64_e32 v[166:167], v[170:171]
	v_mov_b64_e32 v[162:163], v[174:175]
	v_mov_b64_e32 v[168:169], v[172:173]
	v_mov_b64_e32 v[164:165], v[176:177]
.LBB0_1065:
	v_add_f32_e32 v7, v178, v179
	v_add_f32_e32 v148, v180, v181
	v_add_f32_e32 v7, v7, v148
	v_fmaak_f32 v7, v3, v7, 0x358637bd
	v_rsq_f32_e32 v156, v7
	v_cndmask_b32_e64 v7, 0, 1, s[52:53]
	v_cmp_ne_u32_e64 s[8:9], 1, v7
	s_andn2_b64 vcc, exec, s[52:53]
	v_pk_mul_f32 v[150:151], v[140:141], v[156:157] op_sel_hi:[1,0]
	v_pk_mul_f32 v[154:155], v[138:139], v[156:157] op_sel_hi:[1,0]
	v_pk_mul_f32 v[148:149], v[136:137], v[156:157] op_sel_hi:[1,0]
	v_pk_mul_f32 v[152:153], v[134:135], v[156:157] op_sel_hi:[1,0]
	v_pk_mul_f32 v[136:137], v[132:133], v[156:157] op_sel_hi:[1,0]
	v_pk_mul_f32 v[140:141], v[130:131], v[156:157] op_sel_hi:[1,0]
	v_pk_mul_f32 v[134:135], v[128:129], v[156:157] op_sel_hi:[1,0]
	v_pk_mul_f32 v[138:139], v[126:127], v[156:157] op_sel_hi:[1,0]
	s_mov_b64 s[52:53], -1
	s_cbranch_vccnz .LBB0_1075
	s_and_b64 vcc, exec, s[6:7]
	s_cbranch_vccnz .LBB0_1072
	v_lshlrev_b64 v[126:127], 11, v[206:207]
	v_lshl_add_u64 v[126:127], v[4:5], 0, v[126:127]
	s_andn2_b64 vcc, exec, s[26:27]
	s_cbranch_vccnz .LBB0_1069
	v_cvt_pk_bf16_f32 v128, v154, v155
	v_cvt_pk_bf16_f32 v129, v150, v151
	v_cvt_pk_bf16_f32 v130, v152, v153
	v_cvt_pk_bf16_f32 v131, v148, v149
	s_mov_b64 s[52:53], 0
	global_store_dwordx4 v[126:127], v[128:131], off nt
	s_nop 1
	v_cvt_pk_bf16_f32 v128, v140, v141
	v_cvt_pk_bf16_f32 v129, v136, v137
	v_cvt_pk_bf16_f32 v130, v138, v139
	v_cvt_pk_bf16_f32 v131, v134, v135
	global_store_dwordx4 v[126:127], v[128:131], off offset:64 nt
.LBB0_1069:
	s_andn2_b64 vcc, exec, s[52:53]
	s_cbranch_vccnz .LBB0_1071
	v_mul_f32_e32 v7, v155, v155
	v_mul_f32_e32 v128, v151, v151
	v_fmac_f32_e32 v7, v154, v154
	v_fmac_f32_e32 v128, v150, v150
	v_add_f32_e32 v7, v7, v128
	v_mul_f32_e32 v128, v153, v153
	v_mul_f32_e32 v129, v149, v149
	v_fmac_f32_e32 v128, v152, v152
	v_fmac_f32_e32 v129, v148, v148
	v_add_f32_e32 v128, v128, v129
	v_add_f32_e32 v7, v7, v128
	v_mul_f32_e32 v128, v141, v141
	v_mul_f32_e32 v129, v137, v137
	v_fmac_f32_e32 v128, v140, v140
	v_fmac_f32_e32 v129, v136, v136
	v_add_f32_e32 v128, v128, v129
	v_mul_f32_e32 v129, v139, v139
	v_mul_f32_e32 v130, v135, v135
	v_fmac_f32_e32 v129, v138, v138
	v_fmac_f32_e32 v130, v134, v134
	v_add_f32_e32 v129, v129, v130
	v_add_f32_e32 v128, v128, v129
	v_add_f32_e32 v7, v7, v128
	v_mov_b32_e32 v128, v7
	s_nop 1
	v_permlane16_swap_b32_e32 v7, v128
	v_add_f32_e32 v7, v7, v128
	v_mov_b32_e32 v128, v7
	s_nop 1
	v_permlane32_swap_b32_e32 v7, v128
	v_add_f32_e32 v7, v7, v128
	v_fmamk_f32 v7, v7, 0x3c800000, v217
	v_rsq_f32_e32 v7, v7
	v_pk_mul_f32 v[128:129], v[38:39], v[154:155]
	v_pk_mul_f32 v[130:131], v[40:41], v[150:151]
	v_pk_mul_f32 v[156:157], v[34:35], v[152:153]
	v_mul_f32_e32 v128, v128, v7
	v_mul_f32_e32 v129, v129, v7
	v_cvt_pk_bf16_f32 v128, v128, v129
	v_mul_f32_e32 v129, v130, v7
	v_mul_f32_e32 v130, v131, v7
	v_pk_mul_f32 v[132:133], v[36:37], v[148:149]
	v_cvt_pk_bf16_f32 v129, v129, v130
	v_mul_f32_e32 v130, v156, v7
	v_mul_f32_e32 v131, v157, v7
	v_cvt_pk_bf16_f32 v130, v130, v131
	v_mul_f32_e32 v131, v132, v7
	v_mul_f32_e32 v132, v133, v7
	v_cvt_pk_bf16_f32 v131, v131, v132
	global_store_dwordx4 v[126:127], v[128:131], off nt
	v_pk_mul_f32 v[156:157], v[26:27], v[138:139]
	v_pk_mul_f32 v[132:133], v[28:29], v[134:135]
	v_pk_mul_f32 v[128:129], v[30:31], v[140:141]
	v_pk_mul_f32 v[130:131], v[32:33], v[136:137]
	v_mul_f32_e32 v128, v128, v7
	v_mul_f32_e32 v129, v129, v7
	v_cvt_pk_bf16_f32 v128, v128, v129
	v_mul_f32_e32 v129, v130, v7
	v_mul_f32_e32 v130, v131, v7
	v_cvt_pk_bf16_f32 v129, v129, v130
	v_mul_f32_e32 v130, v156, v7
	v_mul_f32_e32 v131, v157, v7
	v_cvt_pk_bf16_f32 v130, v130, v131
	v_mul_f32_e32 v131, v132, v7
	v_mul_f32_e32 v7, v133, v7
	v_cvt_pk_bf16_f32 v131, v131, v7
	global_store_dwordx4 v[126:127], v[128:131], off offset:64 nt

.Lew4_1:
	v_mov_b64_e32 v[126:127], v[162:163]
	v_mov_b64_e32 v[130:131], v[166:167]
	s_andn2_b64 vcc, exec, s[52:53]
	v_mov_b64_e32 v[128:129], v[164:165]
	v_mov_b64_e32 v[132:133], v[168:169]
	s_cbranch_vccnz .LBB0_1074
	v_ashrrev_i32_e32 v7, 31, v204
	v_lshrrev_b32_e32 v7, 19, v7
	v_add_u32_e32 v7, v204, v7
	v_and_b32_e32 v7, 0xffffe000, v7
	v_sub_u32_e32 v126, v204, v7
	v_ashrrev_i32_e32 v127, 31, v126
	v_lshlrev_b64 v[126:127], 7, v[126:127]
	v_lshl_add_u64 v[126:127], v[198:199], 0, v[126:127]
	global_load_dwordx4 v[130:133], v[126:127], off offset:16
	s_nop 0
	global_load_dwordx4 v[126:129], v[126:127], off
	v_mul_f32_e32 v7, v155, v155
	v_mul_f32_e32 v156, v151, v151
	v_fmac_f32_e32 v7, v154, v154
	v_fmac_f32_e32 v156, v150, v150
	v_add_f32_e32 v7, v7, v156
	v_mul_f32_e32 v156, v153, v153
	v_mul_f32_e32 v157, v149, v149
	v_fmac_f32_e32 v156, v152, v152
	v_fmac_f32_e32 v157, v148, v148
	v_add_f32_e32 v156, v156, v157
	v_add_f32_e32 v7, v7, v156
	v_mov_b32_e32 v156, v7
	s_nop 1
	v_permlane16_swap_b32_e32 v7, v156
	v_add_f32_e32 v7, v7, v156
	v_mov_b32_e32 v156, v7
	s_nop 1
	v_permlane32_swap_b32_e32 v7, v156
	v_add_f32_e32 v7, v7, v156
	v_fmamk_f32 v7, v7, 0x3d000000, v217
	v_rsq_f32_e32 v156, v7
	v_mov_b32_e32 v158, v154
	v_mov_b32_e32 v159, v152
	v_mov_b32_e32 v160, v38
	v_pk_mul_f32 v[158:159], v[158:159], v[156:157] op_sel_hi:[1,0]
	v_mov_b32_e32 v161, v34
	v_pk_mul_f32 v[158:159], v[160:161], v[158:159]
	s_nop 0
	v_pk_mul_f32 v[170:171], v[162:163], v[158:159]
	v_pk_mul_f32 v[158:159], v[162:163], v[158:159] op_sel:[1,0] op_sel_hi:[0,1]
	v_add_f32_e32 v157, v158, v159
	v_mov_b32_e32 v158, v155
	v_mov_b32_e32 v159, v153
	v_sub_f32_e32 v7, v170, v171
	v_pk_mul_f32 v[158:159], v[158:159], v[156:157] op_sel_hi:[1,0]
	v_mov_b32_e32 v170, v39
	v_mov_b32_e32 v171, v35
	v_pk_mul_f32 v[158:159], v[170:171], v[158:159]
	v_mul_f32_e32 v176, 0x3e16c740, v157
	v_pk_mul_f32 v[172:173], v[164:165], v[158:159]
	v_pk_mul_f32 v[158:159], v[164:165], v[158:159] op_sel:[1,0] op_sel_hi:[0,1]
	v_sub_f32_e32 v157, v172, v173
	v_mul_f32_e32 v177, 0x3e16c740, v157
	v_add_f32_e32 v157, v158, v159
	v_mov_b32_e32 v158, v150
	v_mov_b32_e32 v159, v148
	v_pk_mul_f32 v[158:159], v[158:159], v[156:157] op_sel_hi:[1,0]
	v_mov_b32_e32 v172, v40
	v_mov_b32_e32 v173, v36
	v_pk_mul_f32 v[158:159], v[172:173], v[158:159]
	v_mul_f32_e32 v178, 0x3e16c740, v157
	v_pk_mul_f32 v[174:175], v[166:167], v[158:159]
	v_pk_mul_f32 v[158:159], v[166:167], v[158:159] op_sel:[1,0] op_sel_hi:[0,1]
	v_sub_f32_e32 v157, v174, v175
	v_mul_f32_e32 v179, 0x3e16c740, v157
	v_add_f32_e32 v157, v158, v159
	v_mov_b32_e32 v158, v151
	v_mov_b32_e32 v159, v149
	v_mul_f32_e32 v180, 0x3e16c740, v157
	v_pk_mul_f32 v[156:157], v[158:159], v[156:157] op_sel_hi:[1,0]
	v_mov_b32_e32 v158, v41
	v_mov_b32_e32 v159, v37
	v_pk_mul_f32 v[156:157], v[158:159], v[156:157]
	v_mul_f32_e32 v7, 0x3e16c740, v7
	v_pk_mul_f32 v[174:175], v[168:169], v[156:157]
	v_pk_mul_f32 v[156:157], v[168:169], v[156:157] op_sel:[1,0] op_sel_hi:[0,1]
	v_add_f32_e32 v156, v156, v157
	v_mul_f32_e32 v181, 0x3e16c740, v156
	v_mov_b64_e32 v[156:157], s[28:29]
	v_sub_f32_e32 v174, v174, v175
	v_mad_i64_i32 v[156:157], s[0:1], v206, s70, v[156:157]
	v_mul_f32_e32 v175, 0x3e16c740, v174
	v_cvt_pk_bf16_f32 v174, v7, v177
	v_lshl_add_u64 v[156:157], v[8:9], 1, v[156:157]
	v_cvt_pk_bf16_f32 v175, v179, v175
	global_store_dwordx2 v[156:157], v[174:175], off offset:128 nt
	v_cvt_pk_bf16_f32 v174, v176, v178
	v_mul_f32_e32 v7, v141, v141
	v_mul_f32_e32 v176, v137, v137
	v_fmac_f32_e32 v7, v140, v140
	v_fmac_f32_e32 v176, v136, v136
	v_add_f32_e32 v7, v7, v176
	v_mul_f32_e32 v176, v139, v139
	v_mul_f32_e32 v177, v135, v135
	v_fmac_f32_e32 v176, v138, v138
	v_fmac_f32_e32 v177, v134, v134
	v_add_f32_e32 v176, v176, v177
	v_add_f32_e32 v7, v7, v176
	v_mov_b32_e32 v176, v7
	s_nop 1
	v_permlane16_swap_b32_e32 v7, v176
	v_add_f32_e32 v7, v7, v176
	v_mov_b32_e32 v176, v7
	s_nop 1
	v_permlane32_swap_b32_e32 v7, v176
	v_add_f32_e32 v7, v7, v176
	v_fmamk_f32 v7, v7, 0x3d000000, v217
	v_rsq_f32_e32 v176, v7
	v_cvt_pk_bf16_f32 v175, v180, v181
	global_store_dwordx2 v[156:157], v[174:175], off offset:160 nt
	v_mov_b32_e32 v174, v140
	v_mov_b32_e32 v175, v138
	v_pk_mul_f32 v[174:175], v[174:175], v[176:177] op_sel_hi:[1,0]
	s_nop 0
	v_pk_mul_f32 v[160:161], v[160:161], v[174:175]
	s_nop 0
	v_pk_mul_f32 v[174:175], v[162:163], v[160:161]
	v_pk_mul_f32 v[160:161], v[162:163], v[160:161] op_sel:[1,0] op_sel_hi:[0,1]
	v_add_f32_e32 v160, v160, v161
	v_sub_f32_e32 v7, v174, v175
	v_mul_f32_e32 v174, 0x3e16c740, v160
	v_mov_b32_e32 v160, v141
	v_mov_b32_e32 v161, v139
	v_pk_mul_f32 v[160:161], v[160:161], v[176:177] op_sel_hi:[1,0]
	v_mul_f32_e32 v7, 0x3e16c740, v7
	v_pk_mul_f32 v[160:161], v[170:171], v[160:161]
	s_nop 0
	v_pk_mul_f32 v[170:171], v[164:165], v[160:161]
	v_pk_mul_f32 v[160:161], v[164:165], v[160:161] op_sel:[1,0] op_sel_hi:[0,1]
	v_add_f32_e32 v160, v160, v161
	v_mul_f32_e32 v177, 0x3e16c740, v160
	v_mov_b32_e32 v160, v136
	v_mov_b32_e32 v161, v134
	v_pk_mul_f32 v[160:161], v[160:161], v[176:177] op_sel_hi:[1,0]
	v_sub_f32_e32 v170, v170, v171
	v_pk_mul_f32 v[160:161], v[172:173], v[160:161]
	v_mul_f32_e32 v175, 0x3e16c740, v170
	v_pk_mul_f32 v[170:171], v[166:167], v[160:161]
	v_pk_mul_f32 v[160:161], v[166:167], v[160:161] op_sel:[1,0] op_sel_hi:[0,1]
	v_add_f32_e32 v160, v160, v161
	v_sub_f32_e32 v170, v170, v171
	v_mul_f32_e32 v171, 0x3e16c740, v160
	v_mov_b32_e32 v160, v137
	v_mov_b32_e32 v161, v135
	v_pk_mul_f32 v[160:161], v[160:161], v[176:177] op_sel_hi:[1,0]
	v_mul_f32_e32 v170, 0x3e16c740, v170
	v_pk_mul_f32 v[158:159], v[158:159], v[160:161]
	s_nop 0
	v_pk_mul_f32 v[160:161], v[168:169], v[158:159]
	v_pk_mul_f32 v[158:159], v[168:169], v[158:159] op_sel:[1,0] op_sel_hi:[0,1]
	v_sub_f32_e32 v160, v160, v161
	v_add_f32_e32 v158, v158, v159
	v_mul_f32_e32 v160, 0x3e16c740, v160
	v_mul_f32_e32 v161, 0x3e16c740, v158
	v_cvt_pk_bf16_f32 v158, v7, v175
	v_cvt_pk_bf16_f32 v159, v170, v160
	global_store_dwordx2 v[156:157], v[158:159], off offset:320 nt
	v_cvt_pk_bf16_f32 v158, v174, v177
	v_cvt_pk_bf16_f32 v159, v171, v161
	global_store_dwordx2 v[156:157], v[158:159], off offset:352 nt

.Lew4_2:
	v_mul_f32_e32 v126, v151, v151
	v_fmac_f32_e32 v7, v154, v154
	v_fmac_f32_e32 v126, v150, v150
	v_add_f32_e32 v7, v7, v126
	v_mul_f32_e32 v126, v153, v153
	v_mul_f32_e32 v127, v149, v149
	v_fmac_f32_e32 v126, v152, v152
	v_fmac_f32_e32 v127, v148, v148
	v_add_f32_e32 v126, v126, v127
	v_add_f32_e32 v7, v7, v126
	v_mul_f32_e32 v126, v141, v141
	v_mul_f32_e32 v127, v137, v137
	v_fmac_f32_e32 v126, v140, v140
	v_fmac_f32_e32 v127, v136, v136
	v_add_f32_e32 v126, v126, v127
	v_mul_f32_e32 v127, v139, v139
	v_mul_f32_e32 v128, v135, v135
	v_fmac_f32_e32 v127, v138, v138
	v_fmac_f32_e32 v128, v134, v134
	v_add_f32_e32 v127, v127, v128
	v_add_f32_e32 v126, v126, v127
	v_add_f32_e32 v7, v7, v126
	v_mov_b32_e32 v126, v7
	s_nop 1
	v_permlane16_swap_b32_e32 v7, v126
	v_add_f32_e32 v7, v7, v126
	v_mov_b32_e32 v126, v7
	s_nop 1
	v_permlane32_swap_b32_e32 v7, v126
	v_add_f32_e32 v7, v7, v126
	v_fmamk_f32 v7, v7, 0x3c800000, v217
	v_rsq_f32_e32 v7, v7
	v_pk_mul_f32 v[126:127], v[38:39], v[154:155]
	v_pk_mul_f32 v[128:129], v[40:41], v[150:151]
	v_pk_mul_f32 v[132:133], v[36:37], v[148:149]
	v_mul_f32_e32 v7, 0x3e16c740, v7
	v_mul_f32_e32 v126, v126, v7
	v_mul_f32_e32 v127, v127, v7
	v_pk_mul_f32 v[148:149], v[34:35], v[152:153]
	v_cvt_pk_bf16_f32 v126, v126, v127
	v_mul_f32_e32 v127, v128, v7
	v_mul_f32_e32 v128, v129, v7
	v_cvt_pk_bf16_f32 v127, v127, v128
	v_mul_f32_e32 v128, v148, v7
	v_mul_f32_e32 v129, v149, v7
	v_mad_i64_i32 v[130:131], s[0:1], v206, s70, v[146:147]
	v_cvt_pk_bf16_f32 v128, v128, v129
	v_mul_f32_e32 v129, v132, v7
	v_mul_f32_e32 v132, v133, v7
	v_cvt_pk_bf16_f32 v129, v129, v132
	global_store_dwordx4 v[130:131], v[126:129], off nt
	v_pk_mul_f32 v[132:133], v[28:29], v[134:135]
	v_pk_mul_f32 v[134:135], v[26:27], v[138:139]
	v_pk_mul_f32 v[126:127], v[30:31], v[140:141]
	v_pk_mul_f32 v[128:129], v[32:33], v[136:137]
	v_mul_f32_e32 v126, v126, v7
	v_mul_f32_e32 v127, v127, v7
	v_cvt_pk_bf16_f32 v126, v126, v127
	v_mul_f32_e32 v127, v128, v7
	v_mul_f32_e32 v128, v129, v7
	v_cvt_pk_bf16_f32 v127, v127, v128
	v_mul_f32_e32 v128, v134, v7
	v_mul_f32_e32 v129, v135, v7
	v_cvt_pk_bf16_f32 v128, v128, v129
	v_mul_f32_e32 v129, v132, v7
	v_mul_f32_e32 v7, v133, v7
	v_cvt_pk_bf16_f32 v129, v129, v7
	global_store_dwordx4 v[130:131], v[126:129], off offset:64 nt
	v_mov_b64_e32 v[130:131], v[166:167]
	v_mov_b64_e32 v[132:133], v[168:169]
	v_mov_b64_e32 v[126:127], v[162:163]
	v_mov_b64_e32 v[128:129], v[164:165]
.LBB0_1077:
	v_add_f32_e32 v7, v142, v143
	v_add_f32_e32 v134, v144, v145
	v_add_f32_e32 v7, v7, v134
	v_fmaak_f32 v7, v3, v7, 0x358637bd
	v_rsq_f32_e32 v142, v7
	s_and_b64 vcc, exec, s[8:9]
	s_mov_b64 s[52:53], -1
	v_pk_mul_f32 v[136:137], v[120:121], v[142:143] op_sel_hi:[1,0]
	v_pk_mul_f32 v[140:141], v[118:119], v[142:143] op_sel_hi:[1,0]
	v_pk_mul_f32 v[134:135], v[116:117], v[142:143] op_sel_hi:[1,0]
	v_pk_mul_f32 v[138:139], v[114:115], v[142:143] op_sel_hi:[1,0]
	v_pk_mul_f32 v[116:117], v[112:113], v[142:143] op_sel_hi:[1,0]
	v_pk_mul_f32 v[120:121], v[110:111], v[142:143] op_sel_hi:[1,0]
	v_pk_mul_f32 v[114:115], v[108:109], v[142:143] op_sel_hi:[1,0]
	v_pk_mul_f32 v[118:119], v[106:107], v[142:143] op_sel_hi:[1,0]
	s_cbranch_vccnz .LBB0_1087
	s_and_b64 vcc, exec, s[6:7]
	s_cbranch_vccnz .LBB0_1084
	v_lshlrev_b64 v[106:107], 11, v[204:205]
	v_lshl_add_u64 v[106:107], v[4:5], 0, v[106:107]
	s_andn2_b64 vcc, exec, s[26:27]
	s_cbranch_vccnz .LBB0_1081
	v_cvt_pk_bf16_f32 v108, v140, v141
	v_cvt_pk_bf16_f32 v109, v136, v137
	v_cvt_pk_bf16_f32 v110, v138, v139
	v_cvt_pk_bf16_f32 v111, v134, v135
	s_mov_b64 s[52:53], 0
	global_store_dwordx4 v[106:107], v[108:111], off nt
	s_nop 1
	v_cvt_pk_bf16_f32 v108, v120, v121
	v_cvt_pk_bf16_f32 v109, v116, v117
	v_cvt_pk_bf16_f32 v110, v118, v119
	v_cvt_pk_bf16_f32 v111, v114, v115
	global_store_dwordx4 v[106:107], v[108:111], off offset:64 nt
.LBB0_1081:
	s_andn2_b64 vcc, exec, s[52:53]
	s_cbranch_vccnz .LBB0_1083
	v_mul_f32_e32 v7, v141, v141
	v_mul_f32_e32 v108, v137, v137
	v_fmac_f32_e32 v7, v140, v140
	v_fmac_f32_e32 v108, v136, v136
	v_add_f32_e32 v7, v7, v108
	v_mul_f32_e32 v108, v139, v139
	v_mul_f32_e32 v109, v135, v135
	v_fmac_f32_e32 v108, v138, v138
	v_fmac_f32_e32 v109, v134, v134
	v_add_f32_e32 v108, v108, v109
	v_add_f32_e32 v7, v7, v108
	v_mul_f32_e32 v108, v121, v121
	v_mul_f32_e32 v109, v117, v117
	v_fmac_f32_e32 v108, v120, v120
	v_fmac_f32_e32 v109, v116, v116
	v_add_f32_e32 v108, v108, v109
	v_mul_f32_e32 v109, v119, v119
	v_mul_f32_e32 v110, v115, v115
	v_fmac_f32_e32 v109, v118, v118
	v_fmac_f32_e32 v110, v114, v114
	v_add_f32_e32 v109, v109, v110
	v_add_f32_e32 v108, v108, v109
	v_add_f32_e32 v7, v7, v108
	v_mov_b32_e32 v108, v7
	s_nop 1
	v_permlane16_swap_b32_e32 v7, v108
	v_add_f32_e32 v7, v7, v108
	v_mov_b32_e32 v108, v7
	s_nop 1
	v_permlane32_swap_b32_e32 v7, v108
	v_add_f32_e32 v7, v7, v108
	v_fmamk_f32 v7, v7, 0x3c800000, v217
	v_rsq_f32_e32 v7, v7
	v_pk_mul_f32 v[108:109], v[38:39], v[140:141]
	v_pk_mul_f32 v[110:111], v[40:41], v[136:137]
	v_pk_mul_f32 v[142:143], v[34:35], v[138:139]
	v_mul_f32_e32 v108, v108, v7
	v_mul_f32_e32 v109, v109, v7
	v_cvt_pk_bf16_f32 v108, v108, v109
	v_mul_f32_e32 v109, v110, v7
	v_mul_f32_e32 v110, v111, v7
	v_pk_mul_f32 v[112:113], v[36:37], v[134:135]
	v_cvt_pk_bf16_f32 v109, v109, v110
	v_mul_f32_e32 v110, v142, v7
	v_mul_f32_e32 v111, v143, v7
	v_cvt_pk_bf16_f32 v110, v110, v111
	v_mul_f32_e32 v111, v112, v7
	v_mul_f32_e32 v112, v113, v7
	v_cvt_pk_bf16_f32 v111, v111, v112
	global_store_dwordx4 v[106:107], v[108:111], off nt
	v_pk_mul_f32 v[142:143], v[26:27], v[118:119]
	v_pk_mul_f32 v[112:113], v[28:29], v[114:115]
	v_pk_mul_f32 v[108:109], v[30:31], v[120:121]
	v_pk_mul_f32 v[110:111], v[32:33], v[116:117]
	v_mul_f32_e32 v108, v108, v7
	v_mul_f32_e32 v109, v109, v7
	v_cvt_pk_bf16_f32 v108, v108, v109
	v_mul_f32_e32 v109, v110, v7
	v_mul_f32_e32 v110, v111, v7
	v_cvt_pk_bf16_f32 v109, v109, v110
	v_mul_f32_e32 v110, v142, v7
	v_mul_f32_e32 v111, v143, v7
	v_cvt_pk_bf16_f32 v110, v110, v111
	v_mul_f32_e32 v111, v112, v7
	v_mul_f32_e32 v7, v113, v7
	v_cvt_pk_bf16_f32 v111, v111, v7
	global_store_dwordx4 v[106:107], v[108:111], off offset:64 nt

.Lew4_3:
	v_mov_b64_e32 v[106:107], v[126:127]
	v_mov_b64_e32 v[110:111], v[130:131]
	s_andn2_b64 vcc, exec, s[52:53]
	v_mov_b64_e32 v[108:109], v[128:129]
	v_mov_b64_e32 v[112:113], v[132:133]
	s_cbranch_vccnz .LBB0_1086
	v_ashrrev_i32_e32 v7, 31, v202
	v_lshrrev_b32_e32 v7, 19, v7
	v_add_u32_e32 v7, v202, v7
	v_and_b32_e32 v7, 0xffffe000, v7
	v_sub_u32_e32 v106, v202, v7
	v_ashrrev_i32_e32 v107, 31, v106
	v_lshlrev_b64 v[106:107], 7, v[106:107]
	v_lshl_add_u64 v[106:107], v[198:199], 0, v[106:107]
	global_load_dwordx4 v[110:113], v[106:107], off offset:16
	s_nop 0
	global_load_dwordx4 v[106:109], v[106:107], off
	v_mul_f32_e32 v7, v141, v141
	v_mul_f32_e32 v142, v137, v137
	v_fmac_f32_e32 v7, v140, v140
	v_fmac_f32_e32 v142, v136, v136
	v_add_f32_e32 v7, v7, v142
	v_mul_f32_e32 v142, v139, v139
	v_mul_f32_e32 v143, v135, v135
	v_fmac_f32_e32 v142, v138, v138
	v_fmac_f32_e32 v143, v134, v134
	v_add_f32_e32 v142, v142, v143
	v_add_f32_e32 v7, v7, v142
	v_mov_b32_e32 v142, v7
	s_nop 1
	v_permlane16_swap_b32_e32 v7, v142
	v_add_f32_e32 v7, v7, v142
	v_mov_b32_e32 v142, v7
	s_nop 1
	v_permlane32_swap_b32_e32 v7, v142
	v_add_f32_e32 v7, v7, v142
	v_fmamk_f32 v7, v7, 0x3d000000, v217
	v_rsq_f32_e32 v142, v7
	v_mov_b32_e32 v144, v140
	v_mov_b32_e32 v145, v138
	v_mov_b32_e32 v148, v38
	v_pk_mul_f32 v[144:145], v[144:145], v[142:143] op_sel_hi:[1,0]
	v_mov_b32_e32 v149, v34
	v_pk_mul_f32 v[144:145], v[148:149], v[144:145]
	s_nop 0
	v_pk_mul_f32 v[150:151], v[126:127], v[144:145]
	v_pk_mul_f32 v[144:145], v[126:127], v[144:145] op_sel:[1,0] op_sel_hi:[0,1]
	v_add_f32_e32 v143, v144, v145
	v_mov_b32_e32 v144, v141
	v_mov_b32_e32 v145, v139
	v_sub_f32_e32 v7, v150, v151
	v_pk_mul_f32 v[144:145], v[144:145], v[142:143] op_sel_hi:[1,0]
	v_mov_b32_e32 v150, v39
	v_mov_b32_e32 v151, v35
	v_pk_mul_f32 v[144:145], v[150:151], v[144:145]
	v_mul_f32_e32 v156, 0x3e16c740, v143
	v_pk_mul_f32 v[152:153], v[128:129], v[144:145]
	v_pk_mul_f32 v[144:145], v[128:129], v[144:145] op_sel:[1,0] op_sel_hi:[0,1]
	v_sub_f32_e32 v143, v152, v153
	v_mul_f32_e32 v157, 0x3e16c740, v143
	v_add_f32_e32 v143, v144, v145
	v_mov_b32_e32 v144, v136
	v_mov_b32_e32 v145, v134
	v_pk_mul_f32 v[144:145], v[144:145], v[142:143] op_sel_hi:[1,0]
	v_mov_b32_e32 v152, v40
	v_mov_b32_e32 v153, v36
	v_pk_mul_f32 v[144:145], v[152:153], v[144:145]
	v_mul_f32_e32 v158, 0x3e16c740, v143
	v_pk_mul_f32 v[154:155], v[130:131], v[144:145]
	v_pk_mul_f32 v[144:145], v[130:131], v[144:145] op_sel:[1,0] op_sel_hi:[0,1]
	v_sub_f32_e32 v143, v154, v155
	v_mul_f32_e32 v159, 0x3e16c740, v143
	v_add_f32_e32 v143, v144, v145
	v_mov_b32_e32 v144, v137
	v_mov_b32_e32 v145, v135
	v_mul_f32_e32 v160, 0x3e16c740, v143
	v_pk_mul_f32 v[142:143], v[144:145], v[142:143] op_sel_hi:[1,0]
	v_mov_b32_e32 v144, v41
	v_mov_b32_e32 v145, v37
	v_pk_mul_f32 v[142:143], v[144:145], v[142:143]
	v_mul_f32_e32 v7, 0x3e16c740, v7
	v_pk_mul_f32 v[154:155], v[132:133], v[142:143]
	v_pk_mul_f32 v[142:143], v[132:133], v[142:143] op_sel:[1,0] op_sel_hi:[0,1]
	v_add_f32_e32 v142, v142, v143
	v_mul_f32_e32 v161, 0x3e16c740, v142
	v_mov_b64_e32 v[142:143], s[28:29]
	v_sub_f32_e32 v154, v154, v155
	v_mad_i64_i32 v[142:143], s[0:1], v204, s70, v[142:143]
	v_mul_f32_e32 v155, 0x3e16c740, v154
	v_cvt_pk_bf16_f32 v154, v7, v157
	v_lshl_add_u64 v[142:143], v[8:9], 1, v[142:143]
	v_cvt_pk_bf16_f32 v155, v159, v155
	global_store_dwordx2 v[142:143], v[154:155], off offset:128 nt
	v_cvt_pk_bf16_f32 v154, v156, v158
	v_mul_f32_e32 v7, v121, v121
	v_mul_f32_e32 v156, v117, v117
	v_fmac_f32_e32 v7, v120, v120
	v_fmac_f32_e32 v156, v116, v116
	v_add_f32_e32 v7, v7, v156
	v_mul_f32_e32 v156, v119, v119
	v_mul_f32_e32 v157, v115, v115
	v_fmac_f32_e32 v156, v118, v118
	v_fmac_f32_e32 v157, v114, v114
	v_add_f32_e32 v156, v156, v157
	v_add_f32_e32 v7, v7, v156
	v_mov_b32_e32 v156, v7
	s_nop 1
	v_permlane16_swap_b32_e32 v7, v156
	v_add_f32_e32 v7, v7, v156
	v_mov_b32_e32 v156, v7
	s_nop 1
	v_permlane32_swap_b32_e32 v7, v156
	v_add_f32_e32 v7, v7, v156
	v_fmamk_f32 v7, v7, 0x3d000000, v217
	v_rsq_f32_e32 v156, v7
	v_cvt_pk_bf16_f32 v155, v160, v161
	global_store_dwordx2 v[142:143], v[154:155], off offset:160 nt
	v_mov_b32_e32 v154, v120
	v_mov_b32_e32 v155, v118
	v_pk_mul_f32 v[154:155], v[154:155], v[156:157] op_sel_hi:[1,0]
	s_nop 0
	v_pk_mul_f32 v[148:149], v[148:149], v[154:155]
	s_nop 0
	v_pk_mul_f32 v[154:155], v[126:127], v[148:149]
	v_pk_mul_f32 v[148:149], v[126:127], v[148:149] op_sel:[1,0] op_sel_hi:[0,1]
	v_add_f32_e32 v148, v148, v149
	v_sub_f32_e32 v7, v154, v155
	v_mul_f32_e32 v154, 0x3e16c740, v148
	v_mov_b32_e32 v148, v121
	v_mov_b32_e32 v149, v119
	v_pk_mul_f32 v[148:149], v[148:149], v[156:157] op_sel_hi:[1,0]
	v_mul_f32_e32 v7, 0x3e16c740, v7
	v_pk_mul_f32 v[148:149], v[150:151], v[148:149]
	s_nop 0
	v_pk_mul_f32 v[150:151], v[128:129], v[148:149]
	v_pk_mul_f32 v[148:149], v[128:129], v[148:149] op_sel:[1,0] op_sel_hi:[0,1]
	v_add_f32_e32 v148, v148, v149
	v_mul_f32_e32 v157, 0x3e16c740, v148
	v_mov_b32_e32 v148, v116
	v_mov_b32_e32 v149, v114
	v_pk_mul_f32 v[148:149], v[148:149], v[156:157] op_sel_hi:[1,0]
	v_sub_f32_e32 v150, v150, v151
	v_pk_mul_f32 v[148:149], v[152:153], v[148:149]
	v_mul_f32_e32 v155, 0x3e16c740, v150
	v_pk_mul_f32 v[150:151], v[130:131], v[148:149]
	v_pk_mul_f32 v[148:149], v[130:131], v[148:149] op_sel:[1,0] op_sel_hi:[0,1]
	v_add_f32_e32 v148, v148, v149
	v_sub_f32_e32 v150, v150, v151
	v_mul_f32_e32 v151, 0x3e16c740, v148
	v_mov_b32_e32 v148, v117
	v_mov_b32_e32 v149, v115
	v_pk_mul_f32 v[148:149], v[148:149], v[156:157] op_sel_hi:[1,0]
	v_mul_f32_e32 v150, 0x3e16c740, v150
	v_pk_mul_f32 v[144:145], v[144:145], v[148:149]
	s_nop 0
	v_pk_mul_f32 v[148:149], v[132:133], v[144:145]
	v_pk_mul_f32 v[144:145], v[132:133], v[144:145] op_sel:[1,0] op_sel_hi:[0,1]
	v_sub_f32_e32 v148, v148, v149
	v_add_f32_e32 v144, v144, v145
	v_mul_f32_e32 v148, 0x3e16c740, v148
	v_mul_f32_e32 v149, 0x3e16c740, v144
	v_cvt_pk_bf16_f32 v144, v7, v155
	v_cvt_pk_bf16_f32 v145, v150, v148
	global_store_dwordx2 v[142:143], v[144:145], off offset:320 nt
	v_cvt_pk_bf16_f32 v144, v154, v157
	v_cvt_pk_bf16_f32 v145, v151, v149
	global_store_dwordx2 v[142:143], v[144:145], off offset:352 nt

.Lew4_4:
	v_mul_f32_e32 v106, v137, v137
	v_fmac_f32_e32 v7, v140, v140
	v_fmac_f32_e32 v106, v136, v136
	v_add_f32_e32 v7, v7, v106
	v_mul_f32_e32 v106, v139, v139
	v_mul_f32_e32 v107, v135, v135
	v_fmac_f32_e32 v106, v138, v138
	v_fmac_f32_e32 v107, v134, v134
	v_add_f32_e32 v106, v106, v107
	v_add_f32_e32 v7, v7, v106
	v_mul_f32_e32 v106, v121, v121
	v_mul_f32_e32 v107, v117, v117
	v_fmac_f32_e32 v106, v120, v120
	v_fmac_f32_e32 v107, v116, v116
	v_add_f32_e32 v106, v106, v107
	v_mul_f32_e32 v107, v119, v119
	v_mul_f32_e32 v108, v115, v115
	v_fmac_f32_e32 v107, v118, v118
	v_fmac_f32_e32 v108, v114, v114
	v_add_f32_e32 v107, v107, v108
	v_add_f32_e32 v106, v106, v107
	v_add_f32_e32 v7, v7, v106
	v_mov_b32_e32 v106, v7
	s_nop 1
	v_permlane16_swap_b32_e32 v7, v106
	v_add_f32_e32 v7, v7, v106
	v_mov_b32_e32 v106, v7
	s_nop 1
	v_permlane32_swap_b32_e32 v7, v106
	v_add_f32_e32 v7, v7, v106
	v_fmamk_f32 v7, v7, 0x3c800000, v217
	v_rsq_f32_e32 v7, v7
	v_pk_mul_f32 v[106:107], v[38:39], v[140:141]
	v_pk_mul_f32 v[108:109], v[40:41], v[136:137]
	v_pk_mul_f32 v[112:113], v[36:37], v[134:135]
	v_mul_f32_e32 v7, 0x3e16c740, v7
	v_mul_f32_e32 v106, v106, v7
	v_mul_f32_e32 v107, v107, v7
	v_pk_mul_f32 v[134:135], v[34:35], v[138:139]
	v_cvt_pk_bf16_f32 v106, v106, v107
	v_mul_f32_e32 v107, v108, v7
	v_mul_f32_e32 v108, v109, v7
	v_cvt_pk_bf16_f32 v107, v107, v108
	v_mul_f32_e32 v108, v134, v7
	v_mul_f32_e32 v109, v135, v7
	v_mad_i64_i32 v[110:111], s[0:1], v204, s70, v[146:147]
	v_cvt_pk_bf16_f32 v108, v108, v109
	v_mul_f32_e32 v109, v112, v7
	v_mul_f32_e32 v112, v113, v7
	v_cvt_pk_bf16_f32 v109, v109, v112
	global_store_dwordx4 v[110:111], v[106:109], off nt
	v_pk_mul_f32 v[112:113], v[28:29], v[114:115]
	v_pk_mul_f32 v[114:115], v[26:27], v[118:119]
	v_pk_mul_f32 v[106:107], v[30:31], v[120:121]
	v_pk_mul_f32 v[108:109], v[32:33], v[116:117]
	v_mul_f32_e32 v106, v106, v7
	v_mul_f32_e32 v107, v107, v7
	v_cvt_pk_bf16_f32 v106, v106, v107
	v_mul_f32_e32 v107, v108, v7
	v_mul_f32_e32 v108, v109, v7
	v_cvt_pk_bf16_f32 v107, v107, v108
	v_mul_f32_e32 v108, v114, v7
	v_mul_f32_e32 v109, v115, v7
	v_cvt_pk_bf16_f32 v108, v108, v109
	v_mul_f32_e32 v109, v112, v7
	v_mul_f32_e32 v7, v113, v7
	v_cvt_pk_bf16_f32 v109, v109, v7
	global_store_dwordx4 v[110:111], v[106:109], off offset:64 nt
	v_mov_b64_e32 v[110:111], v[130:131]
	v_mov_b64_e32 v[112:113], v[132:133]
	v_mov_b64_e32 v[106:107], v[126:127]
	v_mov_b64_e32 v[108:109], v[128:129]
.LBB0_1089:
	v_add_f32_e32 v7, v122, v123
	v_add_f32_e32 v114, v124, v125
	v_add_f32_e32 v7, v7, v114
	v_fmaak_f32 v7, v3, v7, 0x358637bd
	v_rsq_f32_e32 v122, v7
	s_and_b64 vcc, exec, s[8:9]
	s_mov_b64 s[52:53], -1
	v_pk_mul_f32 v[116:117], v[104:105], v[122:123] op_sel_hi:[1,0]
	v_pk_mul_f32 v[120:121], v[102:103], v[122:123] op_sel_hi:[1,0]
	v_pk_mul_f32 v[114:115], v[100:101], v[122:123] op_sel_hi:[1,0]
	v_pk_mul_f32 v[118:119], v[98:99], v[122:123] op_sel_hi:[1,0]
	v_pk_mul_f32 v[96:97], v[96:97], v[122:123] op_sel_hi:[1,0]
	v_pk_mul_f32 v[94:95], v[94:95], v[122:123] op_sel_hi:[1,0]
	v_pk_mul_f32 v[92:93], v[92:93], v[122:123] op_sel_hi:[1,0]
	v_pk_mul_f32 v[90:91], v[90:91], v[122:123] op_sel_hi:[1,0]
	s_cbranch_vccnz .LBB0_1099
	s_and_b64 vcc, exec, s[6:7]
	s_cbranch_vccnz .LBB0_1096
	v_lshlrev_b64 v[98:99], 11, v[202:203]
	v_lshl_add_u64 v[98:99], v[4:5], 0, v[98:99]
	s_andn2_b64 vcc, exec, s[26:27]
	s_cbranch_vccnz .LBB0_1093
	v_cvt_pk_bf16_f32 v100, v120, v121
	v_cvt_pk_bf16_f32 v101, v116, v117
	v_cvt_pk_bf16_f32 v102, v118, v119
	v_cvt_pk_bf16_f32 v103, v114, v115
	s_mov_b64 s[52:53], 0
	global_store_dwordx4 v[98:99], v[100:103], off nt
	s_nop 1
	v_cvt_pk_bf16_f32 v100, v94, v95
	v_cvt_pk_bf16_f32 v101, v96, v97
	v_cvt_pk_bf16_f32 v102, v90, v91
	v_cvt_pk_bf16_f32 v103, v92, v93
	global_store_dwordx4 v[98:99], v[100:103], off offset:64 nt
.LBB0_1093:
	s_andn2_b64 vcc, exec, s[52:53]
	s_cbranch_vccnz .LBB0_1095
	v_mul_f32_e32 v7, v121, v121
	v_mul_f32_e32 v100, v117, v117
	v_fmac_f32_e32 v7, v120, v120
	v_fmac_f32_e32 v100, v116, v116
	v_add_f32_e32 v7, v7, v100
	v_mul_f32_e32 v100, v119, v119
	v_mul_f32_e32 v101, v115, v115
	v_fmac_f32_e32 v100, v118, v118
	v_fmac_f32_e32 v101, v114, v114
	v_add_f32_e32 v100, v100, v101
	v_add_f32_e32 v7, v7, v100
	v_mul_f32_e32 v100, v95, v95
	v_mul_f32_e32 v101, v97, v97
	v_fmac_f32_e32 v100, v94, v94
	v_fmac_f32_e32 v101, v96, v96
	v_add_f32_e32 v100, v100, v101
	v_mul_f32_e32 v101, v91, v91
	v_mul_f32_e32 v102, v93, v93
	v_fmac_f32_e32 v101, v90, v90
	v_fmac_f32_e32 v102, v92, v92
	v_add_f32_e32 v101, v101, v102
	v_add_f32_e32 v100, v100, v101
	v_add_f32_e32 v7, v7, v100
	v_mov_b32_e32 v100, v7
	s_nop 1
	v_permlane16_swap_b32_e32 v7, v100
	v_add_f32_e32 v7, v7, v100
	v_mov_b32_e32 v100, v7
	s_nop 1
	v_permlane32_swap_b32_e32 v7, v100
	v_add_f32_e32 v7, v7, v100
	v_fmamk_f32 v7, v7, 0x3c800000, v217
	v_rsq_f32_e32 v7, v7
	v_pk_mul_f32 v[100:101], v[38:39], v[120:121]
	v_pk_mul_f32 v[102:103], v[40:41], v[116:117]
	v_pk_mul_f32 v[122:123], v[34:35], v[118:119]
	v_mul_f32_e32 v100, v100, v7
	v_mul_f32_e32 v101, v101, v7
	v_cvt_pk_bf16_f32 v100, v100, v101
	v_mul_f32_e32 v101, v102, v7
	v_mul_f32_e32 v102, v103, v7
	v_pk_mul_f32 v[104:105], v[36:37], v[114:115]
	v_cvt_pk_bf16_f32 v101, v101, v102
	v_mul_f32_e32 v102, v122, v7
	v_mul_f32_e32 v103, v123, v7
	v_cvt_pk_bf16_f32 v102, v102, v103
	v_mul_f32_e32 v103, v104, v7
	v_mul_f32_e32 v104, v105, v7
	v_cvt_pk_bf16_f32 v103, v103, v104
	global_store_dwordx4 v[98:99], v[100:103], off nt
	v_pk_mul_f32 v[122:123], v[26:27], v[90:91]
	v_pk_mul_f32 v[104:105], v[28:29], v[92:93]
	v_pk_mul_f32 v[100:101], v[30:31], v[94:95]
	v_pk_mul_f32 v[102:103], v[32:33], v[96:97]
	v_mul_f32_e32 v100, v100, v7
	v_mul_f32_e32 v101, v101, v7
	v_cvt_pk_bf16_f32 v100, v100, v101
	v_mul_f32_e32 v101, v102, v7
	v_mul_f32_e32 v102, v103, v7
	v_cvt_pk_bf16_f32 v101, v101, v102
	v_mul_f32_e32 v102, v122, v7
	v_mul_f32_e32 v103, v123, v7
	v_cvt_pk_bf16_f32 v102, v102, v103
	v_mul_f32_e32 v103, v104, v7
	v_mul_f32_e32 v7, v105, v7
	v_cvt_pk_bf16_f32 v103, v103, v7
	global_store_dwordx4 v[98:99], v[100:103], off offset:64 nt

.Lew4_5:
	v_mov_b64_e32 v[98:99], v[106:107]
	v_mov_b64_e32 v[102:103], v[110:111]
	s_andn2_b64 vcc, exec, s[52:53]
	v_mov_b64_e32 v[100:101], v[108:109]
	v_mov_b64_e32 v[104:105], v[112:113]
	s_cbranch_vccnz .LBB0_1098
	v_add_u32_e32 v7, 0x80, v200
	v_ashrrev_i32_e32 v98, 31, v7
	v_lshrrev_b32_e32 v98, 19, v98
	v_add_u32_e32 v98, v7, v98
	v_and_b32_e32 v98, 0xffffe000, v98
	v_sub_u32_e32 v98, v7, v98
	v_ashrrev_i32_e32 v99, 31, v98
	v_lshlrev_b64 v[98:99], 7, v[98:99]
	v_lshl_add_u64 v[98:99], v[198:199], 0, v[98:99]
	global_load_dwordx4 v[102:105], v[98:99], off offset:16
	s_nop 0
	global_load_dwordx4 v[98:101], v[98:99], off
	v_mul_f32_e32 v7, v121, v121
	v_mul_f32_e32 v122, v117, v117
	v_fmac_f32_e32 v7, v120, v120
	v_fmac_f32_e32 v122, v116, v116
	v_add_f32_e32 v7, v7, v122
	v_mul_f32_e32 v122, v119, v119
	v_mul_f32_e32 v123, v115, v115
	v_fmac_f32_e32 v122, v118, v118
	v_fmac_f32_e32 v123, v114, v114
	v_add_f32_e32 v122, v122, v123
	v_add_f32_e32 v7, v7, v122
	v_mov_b32_e32 v122, v7
	s_nop 1
	v_permlane16_swap_b32_e32 v7, v122
	v_add_f32_e32 v7, v7, v122
	v_mov_b32_e32 v122, v7
	s_nop 1
	v_permlane32_swap_b32_e32 v7, v122
	v_add_f32_e32 v7, v7, v122
	v_fmamk_f32 v7, v7, 0x3d000000, v217
	v_rsq_f32_e32 v122, v7
	v_mov_b32_e32 v124, v120
	v_mov_b32_e32 v125, v118
	v_mov_b32_e32 v126, v38
	v_pk_mul_f32 v[124:125], v[124:125], v[122:123] op_sel_hi:[1,0]
	v_mov_b32_e32 v127, v34
	v_pk_mul_f32 v[124:125], v[126:127], v[124:125]
	s_nop 0
	v_pk_mul_f32 v[128:129], v[106:107], v[124:125]
	v_pk_mul_f32 v[124:125], v[106:107], v[124:125] op_sel:[1,0] op_sel_hi:[0,1]
	v_add_f32_e32 v123, v124, v125
	v_mov_b32_e32 v124, v121
	v_mov_b32_e32 v125, v119
	v_sub_f32_e32 v7, v128, v129
	v_pk_mul_f32 v[124:125], v[124:125], v[122:123] op_sel_hi:[1,0]
	v_mov_b32_e32 v128, v39
	v_mov_b32_e32 v129, v35
	v_pk_mul_f32 v[124:125], v[128:129], v[124:125]
	v_mul_f32_e32 v134, 0x3e16c740, v123
	v_pk_mul_f32 v[130:131], v[108:109], v[124:125]
	v_pk_mul_f32 v[124:125], v[108:109], v[124:125] op_sel:[1,0] op_sel_hi:[0,1]
	v_sub_f32_e32 v123, v130, v131
	v_mul_f32_e32 v135, 0x3e16c740, v123
	v_add_f32_e32 v123, v124, v125
	v_mov_b32_e32 v124, v116
	v_mov_b32_e32 v125, v114
	v_pk_mul_f32 v[124:125], v[124:125], v[122:123] op_sel_hi:[1,0]
	v_mov_b32_e32 v130, v40
	v_mov_b32_e32 v131, v36
	v_pk_mul_f32 v[124:125], v[130:131], v[124:125]
	v_mul_f32_e32 v136, 0x3e16c740, v123
	v_pk_mul_f32 v[132:133], v[110:111], v[124:125]
	v_pk_mul_f32 v[124:125], v[110:111], v[124:125] op_sel:[1,0] op_sel_hi:[0,1]
	v_sub_f32_e32 v123, v132, v133
	v_mul_f32_e32 v137, 0x3e16c740, v123
	v_add_f32_e32 v123, v124, v125
	v_mov_b32_e32 v124, v117
	v_mov_b32_e32 v125, v115
	v_mul_f32_e32 v138, 0x3e16c740, v123
	v_pk_mul_f32 v[122:123], v[124:125], v[122:123] op_sel_hi:[1,0]
	v_mov_b32_e32 v124, v41
	v_mov_b32_e32 v125, v37
	v_pk_mul_f32 v[122:123], v[124:125], v[122:123]
	v_mul_f32_e32 v7, 0x3e16c740, v7
	v_pk_mul_f32 v[132:133], v[112:113], v[122:123]
	v_pk_mul_f32 v[122:123], v[112:113], v[122:123] op_sel:[1,0] op_sel_hi:[0,1]
	v_add_f32_e32 v122, v122, v123
	v_mul_f32_e32 v139, 0x3e16c740, v122
	v_mov_b64_e32 v[122:123], s[28:29]
	v_sub_f32_e32 v132, v132, v133
	v_mad_i64_i32 v[122:123], s[0:1], v202, s70, v[122:123]
	v_mul_f32_e32 v133, 0x3e16c740, v132
	v_cvt_pk_bf16_f32 v132, v7, v135
	v_lshl_add_u64 v[122:123], v[8:9], 1, v[122:123]
	v_cvt_pk_bf16_f32 v133, v137, v133
	global_store_dwordx2 v[122:123], v[132:133], off offset:128 nt
	v_cvt_pk_bf16_f32 v132, v134, v136
	v_mul_f32_e32 v7, v95, v95
	v_mul_f32_e32 v134, v97, v97
	v_fmac_f32_e32 v7, v94, v94
	v_fmac_f32_e32 v134, v96, v96
	v_add_f32_e32 v7, v7, v134
	v_mul_f32_e32 v134, v91, v91
	v_mul_f32_e32 v135, v93, v93
	v_fmac_f32_e32 v134, v90, v90
	v_fmac_f32_e32 v135, v92, v92
	v_add_f32_e32 v134, v134, v135
	v_add_f32_e32 v7, v7, v134
	v_mov_b32_e32 v134, v7
	s_nop 1
	v_permlane16_swap_b32_e32 v7, v134
	v_add_f32_e32 v7, v7, v134
	v_mov_b32_e32 v134, v7
	s_nop 1
	v_permlane32_swap_b32_e32 v7, v134
	v_add_f32_e32 v7, v7, v134
	v_fmamk_f32 v7, v7, 0x3d000000, v217
	v_rsq_f32_e32 v134, v7
	v_cvt_pk_bf16_f32 v133, v138, v139
	global_store_dwordx2 v[122:123], v[132:133], off offset:160 nt
	v_mov_b32_e32 v132, v94
	v_mov_b32_e32 v133, v90
	v_pk_mul_f32 v[132:133], v[132:133], v[134:135] op_sel_hi:[1,0]
	s_nop 0
	v_pk_mul_f32 v[126:127], v[126:127], v[132:133]
	s_nop 0
	v_pk_mul_f32 v[132:133], v[106:107], v[126:127]
	v_pk_mul_f32 v[126:127], v[106:107], v[126:127] op_sel:[1,0] op_sel_hi:[0,1]
	v_add_f32_e32 v126, v126, v127
	v_sub_f32_e32 v7, v132, v133
	v_mul_f32_e32 v132, 0x3e16c740, v126
	v_mov_b32_e32 v126, v95
	v_mov_b32_e32 v127, v91
	v_pk_mul_f32 v[126:127], v[126:127], v[134:135] op_sel_hi:[1,0]
	v_mul_f32_e32 v7, 0x3e16c740, v7
	v_pk_mul_f32 v[126:127], v[128:129], v[126:127]
	s_nop 0
	v_pk_mul_f32 v[128:129], v[108:109], v[126:127]
	v_pk_mul_f32 v[126:127], v[108:109], v[126:127] op_sel:[1,0] op_sel_hi:[0,1]
	v_add_f32_e32 v126, v126, v127
	v_mul_f32_e32 v135, 0x3e16c740, v126
	v_mov_b32_e32 v126, v96
	v_mov_b32_e32 v127, v92
	v_pk_mul_f32 v[126:127], v[126:127], v[134:135] op_sel_hi:[1,0]
	v_sub_f32_e32 v128, v128, v129
	v_pk_mul_f32 v[126:127], v[130:131], v[126:127]
	v_mul_f32_e32 v133, 0x3e16c740, v128
	v_pk_mul_f32 v[128:129], v[110:111], v[126:127]
	v_pk_mul_f32 v[126:127], v[110:111], v[126:127] op_sel:[1,0] op_sel_hi:[0,1]
	v_add_f32_e32 v126, v126, v127
	v_sub_f32_e32 v128, v128, v129
	v_mul_f32_e32 v129, 0x3e16c740, v126
	v_mov_b32_e32 v126, v97
	v_mov_b32_e32 v127, v93
	v_pk_mul_f32 v[126:127], v[126:127], v[134:135] op_sel_hi:[1,0]
	v_mul_f32_e32 v128, 0x3e16c740, v128
	v_pk_mul_f32 v[124:125], v[124:125], v[126:127]
	s_nop 0
	v_pk_mul_f32 v[126:127], v[112:113], v[124:125]
	v_pk_mul_f32 v[124:125], v[112:113], v[124:125] op_sel:[1,0] op_sel_hi:[0,1]
	v_sub_f32_e32 v126, v126, v127
	v_add_f32_e32 v124, v124, v125
	v_mul_f32_e32 v126, 0x3e16c740, v126
	v_mul_f32_e32 v127, 0x3e16c740, v124
	v_cvt_pk_bf16_f32 v124, v7, v133
	v_cvt_pk_bf16_f32 v125, v128, v126
	global_store_dwordx2 v[122:123], v[124:125], off offset:320 nt
	v_cvt_pk_bf16_f32 v124, v132, v135
	v_cvt_pk_bf16_f32 v125, v129, v127
	global_store_dwordx2 v[122:123], v[124:125], off offset:352 nt

.Lew4_6:
	v_mul_f32_e32 v98, v117, v117
	v_fmac_f32_e32 v7, v120, v120
	v_fmac_f32_e32 v98, v116, v116
	v_add_f32_e32 v7, v7, v98
	v_mul_f32_e32 v98, v119, v119
	v_mul_f32_e32 v99, v115, v115
	v_fmac_f32_e32 v98, v118, v118
	v_fmac_f32_e32 v99, v114, v114
	v_add_f32_e32 v98, v98, v99
	v_add_f32_e32 v7, v7, v98
	v_mul_f32_e32 v98, v95, v95
	v_mul_f32_e32 v99, v97, v97
	v_fmac_f32_e32 v98, v94, v94
	v_fmac_f32_e32 v99, v96, v96
	v_add_f32_e32 v98, v98, v99
	v_mul_f32_e32 v99, v91, v91
	v_mul_f32_e32 v100, v93, v93
	v_fmac_f32_e32 v99, v90, v90
	v_fmac_f32_e32 v100, v92, v92
	v_add_f32_e32 v99, v99, v100
	v_add_f32_e32 v98, v98, v99
	v_add_f32_e32 v7, v7, v98
	v_mov_b32_e32 v98, v7
	s_nop 1
	v_permlane16_swap_b32_e32 v7, v98
	v_add_f32_e32 v7, v7, v98
	v_mov_b32_e32 v98, v7
	s_nop 1
	v_permlane32_swap_b32_e32 v7, v98
	v_add_f32_e32 v7, v7, v98
	v_fmamk_f32 v7, v7, 0x3c800000, v217
	v_rsq_f32_e32 v7, v7
	v_pk_mul_f32 v[98:99], v[38:39], v[120:121]
	v_pk_mul_f32 v[100:101], v[40:41], v[116:117]
	v_pk_mul_f32 v[104:105], v[36:37], v[114:115]
	v_mul_f32_e32 v7, 0x3e16c740, v7
	v_mul_f32_e32 v98, v98, v7
	v_mul_f32_e32 v99, v99, v7
	v_pk_mul_f32 v[114:115], v[34:35], v[118:119]
	v_cvt_pk_bf16_f32 v98, v98, v99
	v_mul_f32_e32 v99, v100, v7
	v_mul_f32_e32 v100, v101, v7
	v_cvt_pk_bf16_f32 v99, v99, v100
	v_mul_f32_e32 v100, v114, v7
	v_mul_f32_e32 v101, v115, v7
	v_mad_i64_i32 v[102:103], s[0:1], v202, s70, v[146:147]
	v_cvt_pk_bf16_f32 v100, v100, v101
	v_mul_f32_e32 v101, v104, v7
	v_pk_mul_f32 v[94:95], v[30:31], v[94:95]
	v_mul_f32_e32 v104, v105, v7
	v_cvt_pk_bf16_f32 v101, v101, v104
	global_store_dwordx4 v[102:103], v[98:101], off nt
	v_pk_mul_f32 v[96:97], v[32:33], v[96:97]
	s_nop 0
	v_pk_mul_f32 v[98:99], v[28:29], v[92:93]
	v_pk_mul_f32 v[92:93], v[26:27], v[90:91]
	v_mul_f32_e32 v90, v94, v7
	v_mul_f32_e32 v91, v95, v7
	v_cvt_pk_bf16_f32 v90, v90, v91
	v_mul_f32_e32 v91, v96, v7
	v_mul_f32_e32 v92, v92, v7
	v_mul_f32_e32 v93, v93, v7
	v_mul_f32_e32 v94, v97, v7
	v_cvt_pk_bf16_f32 v91, v91, v94
	v_cvt_pk_bf16_f32 v92, v92, v93
	v_mul_f32_e32 v93, v98, v7
	v_mul_f32_e32 v7, v99, v7
	v_cvt_pk_bf16_f32 v93, v93, v7
	global_store_dwordx4 v[102:103], v[90:93], off offset:64 nt
	v_mov_b64_e32 v[102:103], v[110:111]
	v_mov_b64_e32 v[98:99], v[106:107]
	v_mov_b64_e32 v[104:105], v[112:113]
	v_mov_b64_e32 v[100:101], v[108:109]

.Lew4_8:
	v_mov_b32_e32 v122, v119
	v_mov_b32_e32 v123, v120
	v_mov_b32_e32 v119, v121
	v_pk_add_f32 v[118:119], v[122:123], v[118:119]
	s_nop 0
	v_add_f32_e32 v7, v118, v119
	v_fmaak_f32 v7, v3, v7, 0x358637bd
	v_rsq_f32_e32 v126, v7
	s_nop 0
	v_pk_mul_f32 v[122:123], v[88:89], v[126:127] op_sel_hi:[1,0]
	v_pk_mul_f32 v[124:125], v[86:87], v[126:127] op_sel_hi:[1,0]
	v_pk_mul_f32 v[118:119], v[84:85], v[126:127] op_sel_hi:[1,0]
	v_pk_mul_f32 v[120:121], v[82:83], v[126:127] op_sel_hi:[1,0]
	v_pk_mul_f32 v[86:87], v[80:81], v[126:127] op_sel_hi:[1,0]
	v_pk_mul_f32 v[88:89], v[78:79], v[126:127] op_sel_hi:[1,0]
	v_pk_mul_f32 v[82:83], v[76:77], v[126:127] op_sel_hi:[1,0]
	v_pk_mul_f32 v[84:85], v[74:75], v[126:127] op_sel_hi:[1,0]
	s_cbranch_vccnz .LBB0_1111
	s_and_b64 vcc, exec, s[6:7]
	s_cbranch_vccnz .LBB0_1108
	v_lshlrev_b64 v[74:75], 11, v[116:117]
	v_lshl_add_u64 v[74:75], v[4:5], 0, v[74:75]
	s_andn2_b64 vcc, exec, s[26:27]
	s_cbranch_vccnz .LBB0_1105
	v_cvt_pk_bf16_f32 v76, v124, v125
	v_cvt_pk_bf16_f32 v77, v122, v123
	v_cvt_pk_bf16_f32 v78, v120, v121
	v_cvt_pk_bf16_f32 v79, v118, v119
	s_mov_b64 s[50:51], 0
	global_store_dwordx4 v[74:75], v[76:79], off nt
	s_nop 1
	v_cvt_pk_bf16_f32 v76, v88, v89
	v_cvt_pk_bf16_f32 v77, v86, v87
	v_cvt_pk_bf16_f32 v78, v84, v85
	v_cvt_pk_bf16_f32 v79, v82, v83
	global_store_dwordx4 v[74:75], v[76:79], off offset:64 nt
.LBB0_1105:
	s_andn2_b64 vcc, exec, s[50:51]
	s_cbranch_vccnz .LBB0_1107
	v_mul_f32_e32 v7, v125, v125
	v_mul_f32_e32 v76, v123, v123
	v_fmac_f32_e32 v7, v124, v124
	v_fmac_f32_e32 v76, v122, v122
	v_add_f32_e32 v7, v7, v76
	v_mul_f32_e32 v76, v121, v121
	v_mul_f32_e32 v77, v119, v119
	v_fmac_f32_e32 v76, v120, v120
	v_fmac_f32_e32 v77, v118, v118
	v_add_f32_e32 v76, v76, v77
	v_add_f32_e32 v7, v7, v76
	v_mul_f32_e32 v76, v89, v89
	v_mul_f32_e32 v77, v87, v87
	v_fmac_f32_e32 v76, v88, v88
	v_fmac_f32_e32 v77, v86, v86
	v_add_f32_e32 v76, v76, v77
	v_mul_f32_e32 v77, v85, v85
	v_mul_f32_e32 v78, v83, v83
	v_fmac_f32_e32 v77, v84, v84
	v_fmac_f32_e32 v78, v82, v82
	v_add_f32_e32 v77, v77, v78
	v_add_f32_e32 v76, v76, v77
	v_add_f32_e32 v7, v7, v76
	v_mov_b32_e32 v76, v7
	s_nop 1
	v_permlane16_swap_b32_e32 v7, v76
	v_add_f32_e32 v7, v7, v76
	v_mov_b32_e32 v76, v7
	s_nop 1
	v_permlane32_swap_b32_e32 v7, v76
	v_add_f32_e32 v7, v7, v76
	v_fmamk_f32 v7, v7, 0x3c800000, v217
	v_rsq_f32_e32 v7, v7
	v_pk_mul_f32 v[76:77], v[38:39], v[124:125]
	v_pk_mul_f32 v[78:79], v[40:41], v[122:123]
	v_pk_mul_f32 v[126:127], v[34:35], v[120:121]
	v_mul_f32_e32 v76, v76, v7
	v_mul_f32_e32 v77, v77, v7
	v_cvt_pk_bf16_f32 v76, v76, v77
	v_mul_f32_e32 v77, v78, v7
	v_mul_f32_e32 v78, v79, v7
	v_pk_mul_f32 v[80:81], v[36:37], v[118:119]
	v_cvt_pk_bf16_f32 v77, v77, v78
	v_mul_f32_e32 v78, v126, v7
	v_mul_f32_e32 v79, v127, v7
	v_cvt_pk_bf16_f32 v78, v78, v79
	v_mul_f32_e32 v79, v80, v7
	v_mul_f32_e32 v80, v81, v7
	v_cvt_pk_bf16_f32 v79, v79, v80
	global_store_dwordx4 v[74:75], v[76:79], off nt
	v_pk_mul_f32 v[126:127], v[26:27], v[84:85]
	v_pk_mul_f32 v[80:81], v[28:29], v[82:83]
	v_pk_mul_f32 v[76:77], v[30:31], v[88:89]
	v_pk_mul_f32 v[78:79], v[32:33], v[86:87]
	v_mul_f32_e32 v76, v76, v7
	v_mul_f32_e32 v77, v77, v7
	v_cvt_pk_bf16_f32 v76, v76, v77
	v_mul_f32_e32 v77, v78, v7
	v_mul_f32_e32 v78, v79, v7
	v_cvt_pk_bf16_f32 v77, v77, v78
	v_mul_f32_e32 v78, v126, v7
	v_mul_f32_e32 v79, v127, v7
	v_cvt_pk_bf16_f32 v78, v78, v79
	v_mul_f32_e32 v79, v80, v7
	v_mul_f32_e32 v7, v81, v7
	v_cvt_pk_bf16_f32 v79, v79, v7
	global_store_dwordx4 v[74:75], v[76:79], off offset:64 nt

.LBB0_1108:
	v_mov_b64_e32 v[74:75], v[98:99]
	v_mov_b64_e32 v[78:79], v[102:103]
	s_andn2_b64 vcc, exec, s[50:51]
	v_mov_b64_e32 v[76:77], v[100:101]
	v_mov_b64_e32 v[80:81], v[104:105]
	s_cbranch_vccnz .LBB0_1110
	v_ashrrev_i32_e32 v7, 31, v114
	v_lshrrev_b32_e32 v7, 19, v7
	v_add_u32_e32 v7, v114, v7
	v_and_b32_e32 v7, 0xffffe000, v7
	v_sub_u32_e32 v74, v114, v7
	v_ashrrev_i32_e32 v75, 31, v74
	v_lshlrev_b64 v[74:75], 7, v[74:75]
	v_lshl_add_u64 v[74:75], v[198:199], 0, v[74:75]
	global_load_dwordx4 v[78:81], v[74:75], off offset:16
	s_nop 0
	global_load_dwordx4 v[74:77], v[74:75], off
	v_mul_f32_e32 v7, v125, v125
	v_mul_f32_e32 v117, v123, v123
	v_fmac_f32_e32 v7, v124, v124
	v_fmac_f32_e32 v117, v122, v122
	v_add_f32_e32 v7, v7, v117
	v_mul_f32_e32 v117, v121, v121
	v_mul_f32_e32 v126, v119, v119
	v_fmac_f32_e32 v117, v120, v120
	v_fmac_f32_e32 v126, v118, v118
	v_add_f32_e32 v117, v117, v126
	v_add_f32_e32 v7, v7, v117
	v_mov_b32_e32 v117, v7
	s_nop 1
	v_permlane16_swap_b32_e32 v7, v117
	v_add_f32_e32 v7, v7, v117
	v_mov_b32_e32 v117, v7
	s_nop 1
	v_permlane32_swap_b32_e32 v7, v117
	v_add_f32_e32 v7, v7, v117
	v_fmamk_f32 v7, v7, 0x3d000000, v217
	v_rsq_f32_e32 v126, v7
	v_mov_b32_e32 v128, v124
	v_mov_b32_e32 v129, v120
	v_mov_b32_e32 v130, v38
	v_pk_mul_f32 v[128:129], v[128:129], v[126:127] op_sel_hi:[1,0]
	v_mov_b32_e32 v131, v34
	v_pk_mul_f32 v[128:129], v[130:131], v[128:129]
	s_nop 0
	v_pk_mul_f32 v[132:133], v[98:99], v[128:129]
	v_pk_mul_f32 v[128:129], v[98:99], v[128:129] op_sel:[1,0] op_sel_hi:[0,1]
	v_add_f32_e32 v117, v128, v129
	v_mov_b32_e32 v128, v125
	v_mov_b32_e32 v129, v121
	v_sub_f32_e32 v7, v132, v133
	v_pk_mul_f32 v[128:129], v[128:129], v[126:127] op_sel_hi:[1,0]
	v_mov_b32_e32 v132, v39
	v_mov_b32_e32 v133, v35
	v_pk_mul_f32 v[128:129], v[132:133], v[128:129]
	v_mul_f32_e32 v7, 0x3e16c740, v7
	v_pk_mul_f32 v[134:135], v[100:101], v[128:129]
	v_pk_mul_f32 v[128:129], v[100:101], v[128:129] op_sel:[1,0] op_sel_hi:[0,1]
	v_sub_f32_e32 v127, v134, v135
	v_mul_f32_e32 v138, 0x3e16c740, v127
	v_add_f32_e32 v127, v128, v129
	v_mov_b32_e32 v128, v122
	v_mov_b32_e32 v129, v118
	v_pk_mul_f32 v[128:129], v[128:129], v[126:127] op_sel_hi:[1,0]
	v_mov_b32_e32 v134, v40
	v_mov_b32_e32 v135, v36
	v_pk_mul_f32 v[128:129], v[134:135], v[128:129]
	v_mul_f32_e32 v139, 0x3e16c740, v127
	v_pk_mul_f32 v[136:137], v[102:103], v[128:129]
	v_pk_mul_f32 v[128:129], v[102:103], v[128:129] op_sel:[1,0] op_sel_hi:[0,1]
	v_sub_f32_e32 v127, v136, v137
	v_mul_f32_e32 v140, 0x3e16c740, v127
	v_add_f32_e32 v127, v128, v129
	v_mov_b32_e32 v128, v123
	v_mov_b32_e32 v129, v119
	v_mul_f32_e32 v141, 0x3e16c740, v127
	v_pk_mul_f32 v[126:127], v[128:129], v[126:127] op_sel_hi:[1,0]
	v_mov_b32_e32 v128, v41
	v_mov_b32_e32 v129, v37
	v_pk_mul_f32 v[126:127], v[128:129], v[126:127]
	v_mul_f32_e32 v117, 0x3e16c740, v117
	v_pk_mul_f32 v[136:137], v[104:105], v[126:127]
	v_pk_mul_f32 v[126:127], v[104:105], v[126:127] op_sel:[1,0] op_sel_hi:[0,1]
	v_add_f32_e32 v126, v126, v127
	v_mul_f32_e32 v142, 0x3e16c740, v126
	v_mov_b64_e32 v[126:127], s[28:29]
	v_sub_f32_e32 v136, v136, v137
	v_mad_i64_i32 v[126:127], s[0:1], v116, s70, v[126:127]
	v_mul_f32_e32 v137, 0x3e16c740, v136
	v_cvt_pk_bf16_f32 v136, v7, v138
	v_lshl_add_u64 v[126:127], v[8:9], 1, v[126:127]
	v_cvt_pk_bf16_f32 v137, v140, v137
	global_store_dwordx2 v[126:127], v[136:137], off offset:128 nt
	v_cvt_pk_bf16_f32 v136, v117, v139
	v_mul_f32_e32 v7, v89, v89
	v_mul_f32_e32 v117, v87, v87
	v_fmac_f32_e32 v7, v88, v88
	v_fmac_f32_e32 v117, v86, v86
	v_add_f32_e32 v7, v7, v117
	v_mul_f32_e32 v117, v85, v85
	v_mul_f32_e32 v138, v83, v83
	v_fmac_f32_e32 v117, v84, v84
	v_fmac_f32_e32 v138, v82, v82
	v_add_f32_e32 v117, v117, v138
	v_add_f32_e32 v7, v7, v117
	v_mov_b32_e32 v117, v7
	s_nop 1
	v_permlane16_swap_b32_e32 v7, v117
	v_add_f32_e32 v7, v7, v117
	v_mov_b32_e32 v117, v7
	s_nop 1
	v_permlane32_swap_b32_e32 v7, v117
	v_add_f32_e32 v7, v7, v117
	v_fmamk_f32 v7, v7, 0x3d000000, v217
	v_rsq_f32_e32 v138, v7
	v_cvt_pk_bf16_f32 v137, v141, v142
	global_store_dwordx2 v[126:127], v[136:137], off offset:160 nt
	v_mov_b32_e32 v136, v88
	v_mov_b32_e32 v137, v84
	v_pk_mul_f32 v[136:137], v[136:137], v[138:139] op_sel_hi:[1,0]
	s_nop 0
	v_pk_mul_f32 v[130:131], v[130:131], v[136:137]
	s_nop 0
	v_pk_mul_f32 v[136:137], v[98:99], v[130:131]
	v_pk_mul_f32 v[130:131], v[98:99], v[130:131] op_sel:[1,0] op_sel_hi:[0,1]
	v_add_f32_e32 v117, v130, v131
	v_mov_b32_e32 v130, v89
	v_mov_b32_e32 v131, v85
	v_pk_mul_f32 v[130:131], v[130:131], v[138:139] op_sel_hi:[1,0]
	v_sub_f32_e32 v7, v136, v137
	v_pk_mul_f32 v[130:131], v[132:133], v[130:131]
	v_mul_f32_e32 v7, 0x3e16c740, v7
	v_pk_mul_f32 v[132:133], v[100:101], v[130:131]
	v_pk_mul_f32 v[130:131], v[100:101], v[130:131] op_sel:[1,0] op_sel_hi:[0,1]
	v_add_f32_e32 v130, v130, v131
	v_mul_f32_e32 v137, 0x3e16c740, v130
	v_mov_b32_e32 v130, v86
	v_mov_b32_e32 v131, v82
	v_pk_mul_f32 v[130:131], v[130:131], v[138:139] op_sel_hi:[1,0]
	v_sub_f32_e32 v132, v132, v133
	v_pk_mul_f32 v[130:131], v[134:135], v[130:131]
	v_mul_f32_e32 v136, 0x3e16c740, v132
	v_pk_mul_f32 v[132:133], v[102:103], v[130:131]
	v_pk_mul_f32 v[130:131], v[102:103], v[130:131] op_sel:[1,0] op_sel_hi:[0,1]
	v_add_f32_e32 v130, v130, v131
	v_sub_f32_e32 v132, v132, v133
	v_mul_f32_e32 v133, 0x3e16c740, v130
	v_mov_b32_e32 v130, v87
	v_mov_b32_e32 v131, v83
	v_pk_mul_f32 v[130:131], v[130:131], v[138:139] op_sel_hi:[1,0]
	v_mul_f32_e32 v132, 0x3e16c740, v132
	v_pk_mul_f32 v[128:129], v[128:129], v[130:131]
	v_mul_f32_e32 v117, 0x3e16c740, v117
	v_pk_mul_f32 v[130:131], v[104:105], v[128:129]
	v_pk_mul_f32 v[128:129], v[104:105], v[128:129] op_sel:[1,0] op_sel_hi:[0,1]
	v_sub_f32_e32 v130, v130, v131
	v_add_f32_e32 v128, v128, v129
	v_mul_f32_e32 v130, 0x3e16c740, v130
	v_mul_f32_e32 v131, 0x3e16c740, v128
	v_cvt_pk_bf16_f32 v128, v7, v136
	v_cvt_pk_bf16_f32 v129, v132, v130
	global_store_dwordx2 v[126:127], v[128:129], off offset:320 nt
	v_cvt_pk_bf16_f32 v128, v117, v137
	v_cvt_pk_bf16_f32 v129, v133, v131
	global_store_dwordx2 v[126:127], v[128:129], off offset:352 nt

.Lew4_9:
	v_mul_f32_e32 v74, v123, v123
	v_fmac_f32_e32 v7, v124, v124
	v_fmac_f32_e32 v74, v122, v122
	v_add_f32_e32 v7, v7, v74
	v_mul_f32_e32 v74, v121, v121
	v_mul_f32_e32 v75, v119, v119
	v_fmac_f32_e32 v74, v120, v120
	v_fmac_f32_e32 v75, v118, v118
	v_add_f32_e32 v74, v74, v75
	v_add_f32_e32 v7, v7, v74
	v_mul_f32_e32 v74, v89, v89
	v_mul_f32_e32 v75, v87, v87
	v_fmac_f32_e32 v74, v88, v88
	v_fmac_f32_e32 v75, v86, v86
	v_add_f32_e32 v74, v74, v75
	v_mul_f32_e32 v75, v85, v85
	v_mul_f32_e32 v76, v83, v83
	v_fmac_f32_e32 v75, v84, v84
	v_fmac_f32_e32 v76, v82, v82
	v_add_f32_e32 v75, v75, v76
	v_add_f32_e32 v74, v74, v75
	v_add_f32_e32 v7, v7, v74
	v_mov_b32_e32 v74, v7
	s_nop 1
	v_permlane16_swap_b32_e32 v7, v74
	v_add_f32_e32 v7, v7, v74
	v_mov_b32_e32 v74, v7
	s_nop 1
	v_permlane32_swap_b32_e32 v7, v74
	v_add_f32_e32 v7, v7, v74
	v_fmamk_f32 v7, v7, 0x3c800000, v217
	v_rsq_f32_e32 v7, v7
	v_pk_mul_f32 v[74:75], v[38:39], v[124:125]
	v_pk_mul_f32 v[76:77], v[40:41], v[122:123]
	v_mad_i64_i32 v[78:79], s[0:1], v116, s70, v[146:147]
	v_mul_f32_e32 v7, 0x3e16c740, v7
	v_mul_f32_e32 v74, v74, v7
	v_mul_f32_e32 v75, v75, v7
	v_pk_mul_f32 v[116:117], v[34:35], v[120:121]
	v_cvt_pk_bf16_f32 v74, v74, v75
	v_mul_f32_e32 v75, v76, v7
	v_mul_f32_e32 v76, v77, v7
	v_pk_mul_f32 v[80:81], v[36:37], v[118:119]
	v_cvt_pk_bf16_f32 v75, v75, v76
	v_mul_f32_e32 v76, v116, v7
	v_mul_f32_e32 v77, v117, v7
	v_cvt_pk_bf16_f32 v76, v76, v77
	v_mul_f32_e32 v77, v80, v7
	v_mul_f32_e32 v80, v81, v7
	v_cvt_pk_bf16_f32 v77, v77, v80
	global_store_dwordx4 v[78:79], v[74:77], off nt
	v_pk_mul_f32 v[80:81], v[28:29], v[82:83]
	v_pk_mul_f32 v[82:83], v[26:27], v[84:85]
	v_pk_mul_f32 v[74:75], v[30:31], v[88:89]
	v_pk_mul_f32 v[76:77], v[32:33], v[86:87]
	v_mul_f32_e32 v74, v74, v7
	v_mul_f32_e32 v75, v75, v7
	v_cvt_pk_bf16_f32 v74, v74, v75
	v_mul_f32_e32 v75, v76, v7
	v_mul_f32_e32 v76, v77, v7
	v_cvt_pk_bf16_f32 v75, v75, v76
	v_mul_f32_e32 v76, v82, v7
	v_mul_f32_e32 v77, v83, v7
	v_cvt_pk_bf16_f32 v76, v76, v77
	v_mul_f32_e32 v77, v80, v7
	v_mul_f32_e32 v7, v81, v7
	v_cvt_pk_bf16_f32 v77, v77, v7
	global_store_dwordx4 v[78:79], v[74:77], off offset:64 nt
	v_mov_b64_e32 v[78:79], v[102:103]
	v_mov_b64_e32 v[80:81], v[104:105]
	v_mov_b64_e32 v[74:75], v[98:99]
	v_mov_b64_e32 v[76:77], v[100:101]

.Lew4_10:
	v_add_f32_e32 v7, v106, v107
	v_add_f32_e32 v82, v108, v109
	v_add_f32_e32 v7, v7, v82
	v_fmaak_f32 v7, v3, v7, 0x358637bd
	v_rsq_f32_e32 v98, v7
	s_and_b64 vcc, exec, s[8:9]
	s_mov_b64 s[50:51], -1
	v_pk_mul_f32 v[84:85], v[72:73], v[98:99] op_sel_hi:[1,0]
	v_pk_mul_f32 v[88:89], v[70:71], v[98:99] op_sel_hi:[1,0]
	v_pk_mul_f32 v[82:83], v[68:69], v[98:99] op_sel_hi:[1,0]
	v_pk_mul_f32 v[86:87], v[66:67], v[98:99] op_sel_hi:[1,0]
	v_pk_mul_f32 v[68:69], v[64:65], v[98:99] op_sel_hi:[1,0]
	v_pk_mul_f32 v[72:73], v[62:63], v[98:99] op_sel_hi:[1,0]
	v_pk_mul_f32 v[66:67], v[60:61], v[98:99] op_sel_hi:[1,0]
	v_pk_mul_f32 v[70:71], v[58:59], v[98:99] op_sel_hi:[1,0]
	s_cbranch_vccnz .LBB0_1123
	s_and_b64 vcc, exec, s[6:7]
	s_cbranch_vccnz .LBB0_1120
	v_lshlrev_b64 v[58:59], 11, v[114:115]
	v_lshl_add_u64 v[58:59], v[4:5], 0, v[58:59]
	s_andn2_b64 vcc, exec, s[26:27]
	s_cbranch_vccnz .LBB0_1117
	v_cvt_pk_bf16_f32 v60, v88, v89
	v_cvt_pk_bf16_f32 v61, v84, v85
	v_cvt_pk_bf16_f32 v62, v86, v87
	v_cvt_pk_bf16_f32 v63, v82, v83
	s_mov_b64 s[50:51], 0
	global_store_dwordx4 v[58:59], v[60:63], off nt
	s_nop 1
	v_cvt_pk_bf16_f32 v60, v72, v73
	v_cvt_pk_bf16_f32 v61, v68, v69
	v_cvt_pk_bf16_f32 v62, v70, v71
	v_cvt_pk_bf16_f32 v63, v66, v67
	global_store_dwordx4 v[58:59], v[60:63], off offset:64 nt
.LBB0_1117:
	s_andn2_b64 vcc, exec, s[50:51]
	s_cbranch_vccnz .LBB0_1119
	v_mul_f32_e32 v7, v89, v89
	v_mul_f32_e32 v60, v85, v85
	v_fmac_f32_e32 v7, v88, v88
	v_fmac_f32_e32 v60, v84, v84
	v_add_f32_e32 v7, v7, v60
	v_mul_f32_e32 v60, v87, v87
	v_mul_f32_e32 v61, v83, v83
	v_fmac_f32_e32 v60, v86, v86
	v_fmac_f32_e32 v61, v82, v82
	v_add_f32_e32 v60, v60, v61
	v_add_f32_e32 v7, v7, v60
	v_mul_f32_e32 v60, v73, v73
	v_mul_f32_e32 v61, v69, v69
	v_fmac_f32_e32 v60, v72, v72
	v_fmac_f32_e32 v61, v68, v68
	v_add_f32_e32 v60, v60, v61
	v_mul_f32_e32 v61, v71, v71
	v_mul_f32_e32 v62, v67, v67
	v_fmac_f32_e32 v61, v70, v70
	v_fmac_f32_e32 v62, v66, v66
	v_add_f32_e32 v61, v61, v62
	v_add_f32_e32 v60, v60, v61
	v_add_f32_e32 v7, v7, v60
	v_mov_b32_e32 v60, v7
	s_nop 1
	v_permlane16_swap_b32_e32 v7, v60
	v_add_f32_e32 v7, v7, v60
	v_mov_b32_e32 v60, v7
	s_nop 1
	v_permlane32_swap_b32_e32 v7, v60
	v_add_f32_e32 v7, v7, v60
	v_fmamk_f32 v7, v7, 0x3c800000, v217
	v_rsq_f32_e32 v7, v7
	v_pk_mul_f32 v[60:61], v[38:39], v[88:89]
	v_pk_mul_f32 v[62:63], v[40:41], v[84:85]
	v_pk_mul_f32 v[98:99], v[34:35], v[86:87]
	v_mul_f32_e32 v60, v60, v7
	v_mul_f32_e32 v61, v61, v7
	v_cvt_pk_bf16_f32 v60, v60, v61
	v_mul_f32_e32 v61, v62, v7
	v_mul_f32_e32 v62, v63, v7
	v_pk_mul_f32 v[64:65], v[36:37], v[82:83]
	v_cvt_pk_bf16_f32 v61, v61, v62
	v_mul_f32_e32 v62, v98, v7
	v_mul_f32_e32 v63, v99, v7
	v_cvt_pk_bf16_f32 v62, v62, v63
	v_mul_f32_e32 v63, v64, v7
	v_mul_f32_e32 v64, v65, v7
	v_cvt_pk_bf16_f32 v63, v63, v64
	global_store_dwordx4 v[58:59], v[60:63], off nt
	v_pk_mul_f32 v[98:99], v[26:27], v[70:71]
	v_pk_mul_f32 v[64:65], v[28:29], v[66:67]
	v_pk_mul_f32 v[60:61], v[30:31], v[72:73]
	v_pk_mul_f32 v[62:63], v[32:33], v[68:69]
	v_mul_f32_e32 v60, v60, v7
	v_mul_f32_e32 v61, v61, v7
	v_cvt_pk_bf16_f32 v60, v60, v61
	v_mul_f32_e32 v61, v62, v7
	v_mul_f32_e32 v62, v63, v7
	v_cvt_pk_bf16_f32 v61, v61, v62
	v_mul_f32_e32 v62, v98, v7
	v_mul_f32_e32 v63, v99, v7
	v_cvt_pk_bf16_f32 v62, v62, v63
	v_mul_f32_e32 v63, v64, v7
	v_mul_f32_e32 v7, v65, v7
	v_cvt_pk_bf16_f32 v63, v63, v7
	global_store_dwordx4 v[58:59], v[60:63], off offset:64 nt

.LBB0_1120:
	v_mov_b64_e32 v[58:59], v[74:75]
	v_mov_b64_e32 v[62:63], v[78:79]
	s_andn2_b64 vcc, exec, s[50:51]
	v_mov_b64_e32 v[60:61], v[76:77]
	v_mov_b64_e32 v[64:65], v[80:81]
	s_cbranch_vccnz .LBB0_1122
	v_ashrrev_i32_e32 v7, 31, v112
	v_lshrrev_b32_e32 v7, 19, v7
	v_add_u32_e32 v7, v112, v7
	v_and_b32_e32 v7, 0xffffe000, v7
	v_sub_u32_e32 v58, v112, v7
	v_ashrrev_i32_e32 v59, 31, v58
	v_lshlrev_b64 v[58:59], 7, v[58:59]
	v_lshl_add_u64 v[58:59], v[198:199], 0, v[58:59]
	global_load_dwordx4 v[62:65], v[58:59], off offset:16
	s_nop 0
	global_load_dwordx4 v[58:61], v[58:59], off
	v_mul_f32_e32 v7, v89, v89
	v_mul_f32_e32 v98, v85, v85
	v_fmac_f32_e32 v7, v88, v88
	v_fmac_f32_e32 v98, v84, v84
	v_add_f32_e32 v7, v7, v98
	v_mul_f32_e32 v98, v87, v87
	v_mul_f32_e32 v99, v83, v83
	v_fmac_f32_e32 v98, v86, v86
	v_fmac_f32_e32 v99, v82, v82
	v_add_f32_e32 v98, v98, v99
	v_add_f32_e32 v7, v7, v98
	v_mov_b32_e32 v98, v7
	s_nop 1
	v_permlane16_swap_b32_e32 v7, v98
	v_add_f32_e32 v7, v7, v98
	v_mov_b32_e32 v98, v7
	s_nop 1
	v_permlane32_swap_b32_e32 v7, v98
	v_add_f32_e32 v7, v7, v98
	v_fmamk_f32 v7, v7, 0x3d000000, v217
	v_rsq_f32_e32 v98, v7
	v_mov_b32_e32 v100, v88
	v_mov_b32_e32 v101, v86
	v_mov_b32_e32 v102, v38
	v_pk_mul_f32 v[100:101], v[100:101], v[98:99] op_sel_hi:[1,0]
	v_mov_b32_e32 v103, v34
	v_pk_mul_f32 v[100:101], v[102:103], v[100:101]
	s_nop 0
	v_pk_mul_f32 v[104:105], v[74:75], v[100:101]
	v_pk_mul_f32 v[100:101], v[74:75], v[100:101] op_sel:[1,0] op_sel_hi:[0,1]
	v_add_f32_e32 v99, v100, v101
	v_mov_b32_e32 v100, v89
	v_mov_b32_e32 v101, v87
	v_sub_f32_e32 v7, v104, v105
	v_pk_mul_f32 v[100:101], v[100:101], v[98:99] op_sel_hi:[1,0]
	v_mov_b32_e32 v104, v39
	v_mov_b32_e32 v105, v35
	v_pk_mul_f32 v[100:101], v[104:105], v[100:101]
	v_mul_f32_e32 v115, 0x3e16c740, v99
	v_pk_mul_f32 v[106:107], v[76:77], v[100:101]
	v_pk_mul_f32 v[100:101], v[76:77], v[100:101] op_sel:[1,0] op_sel_hi:[0,1]
	v_sub_f32_e32 v99, v106, v107
	v_mul_f32_e32 v116, 0x3e16c740, v99
	v_add_f32_e32 v99, v100, v101
	v_mov_b32_e32 v100, v84
	v_mov_b32_e32 v101, v82
	v_pk_mul_f32 v[100:101], v[100:101], v[98:99] op_sel_hi:[1,0]
	v_mov_b32_e32 v106, v40
	v_mov_b32_e32 v107, v36
	v_pk_mul_f32 v[100:101], v[106:107], v[100:101]
	v_mul_f32_e32 v117, 0x3e16c740, v99
	v_pk_mul_f32 v[108:109], v[78:79], v[100:101]
	v_pk_mul_f32 v[100:101], v[78:79], v[100:101] op_sel:[1,0] op_sel_hi:[0,1]
	v_sub_f32_e32 v99, v108, v109
	v_mul_f32_e32 v118, 0x3e16c740, v99
	v_add_f32_e32 v99, v100, v101
	v_mov_b32_e32 v100, v85
	v_mov_b32_e32 v101, v83
	v_mul_f32_e32 v119, 0x3e16c740, v99
	v_pk_mul_f32 v[98:99], v[100:101], v[98:99] op_sel_hi:[1,0]
	v_mov_b32_e32 v100, v41
	v_mov_b32_e32 v101, v37
	v_pk_mul_f32 v[98:99], v[100:101], v[98:99]
	v_mul_f32_e32 v7, 0x3e16c740, v7
	v_pk_mul_f32 v[108:109], v[80:81], v[98:99]
	v_pk_mul_f32 v[98:99], v[80:81], v[98:99] op_sel:[1,0] op_sel_hi:[0,1]
	v_add_f32_e32 v98, v98, v99
	v_mul_f32_e32 v120, 0x3e16c740, v98
	v_mov_b64_e32 v[98:99], s[28:29]
	v_sub_f32_e32 v108, v108, v109
	v_mad_i64_i32 v[98:99], s[0:1], v114, s70, v[98:99]
	v_mul_f32_e32 v109, 0x3e16c740, v108
	v_cvt_pk_bf16_f32 v108, v7, v116
	v_lshl_add_u64 v[98:99], v[8:9], 1, v[98:99]
	v_cvt_pk_bf16_f32 v109, v118, v109
	global_store_dwordx2 v[98:99], v[108:109], off offset:128 nt
	v_cvt_pk_bf16_f32 v108, v115, v117
	v_mul_f32_e32 v7, v73, v73
	v_mul_f32_e32 v115, v69, v69
	v_fmac_f32_e32 v7, v72, v72
	v_fmac_f32_e32 v115, v68, v68
	v_add_f32_e32 v7, v7, v115
	v_mul_f32_e32 v115, v71, v71
	v_mul_f32_e32 v116, v67, v67
	v_fmac_f32_e32 v115, v70, v70
	v_fmac_f32_e32 v116, v66, v66
	v_add_f32_e32 v115, v115, v116
	v_add_f32_e32 v7, v7, v115
	v_mov_b32_e32 v115, v7
	s_nop 1
	v_permlane16_swap_b32_e32 v7, v115
	v_add_f32_e32 v7, v7, v115
	v_mov_b32_e32 v115, v7
	s_nop 1
	v_permlane32_swap_b32_e32 v7, v115
	v_add_f32_e32 v7, v7, v115
	v_fmamk_f32 v7, v7, 0x3d000000, v217
	v_rsq_f32_e32 v116, v7
	v_cvt_pk_bf16_f32 v109, v119, v120
	global_store_dwordx2 v[98:99], v[108:109], off offset:160 nt
	v_mov_b32_e32 v108, v72
	v_mov_b32_e32 v109, v70
	v_pk_mul_f32 v[108:109], v[108:109], v[116:117] op_sel_hi:[1,0]
	s_nop 0
	v_pk_mul_f32 v[102:103], v[102:103], v[108:109]
	s_nop 0
	v_pk_mul_f32 v[108:109], v[74:75], v[102:103]
	v_pk_mul_f32 v[102:103], v[74:75], v[102:103] op_sel:[1,0] op_sel_hi:[0,1]
	v_add_f32_e32 v102, v102, v103
	v_sub_f32_e32 v7, v108, v109
	v_mul_f32_e32 v108, 0x3e16c740, v102
	v_mov_b32_e32 v102, v73
	v_mov_b32_e32 v103, v71
	v_pk_mul_f32 v[102:103], v[102:103], v[116:117] op_sel_hi:[1,0]
	v_mul_f32_e32 v7, 0x3e16c740, v7
	v_pk_mul_f32 v[102:103], v[104:105], v[102:103]
	s_nop 0
	v_pk_mul_f32 v[104:105], v[76:77], v[102:103]
	v_pk_mul_f32 v[102:103], v[76:77], v[102:103] op_sel:[1,0] op_sel_hi:[0,1]
	v_add_f32_e32 v102, v102, v103
	v_mul_f32_e32 v115, 0x3e16c740, v102
	v_mov_b32_e32 v102, v68
	v_mov_b32_e32 v103, v66
	v_pk_mul_f32 v[102:103], v[102:103], v[116:117] op_sel_hi:[1,0]
	v_sub_f32_e32 v104, v104, v105
	v_pk_mul_f32 v[102:103], v[106:107], v[102:103]
	v_mul_f32_e32 v109, 0x3e16c740, v104
	v_pk_mul_f32 v[104:105], v[78:79], v[102:103]
	v_pk_mul_f32 v[102:103], v[78:79], v[102:103] op_sel:[1,0] op_sel_hi:[0,1]
	v_add_f32_e32 v102, v102, v103
	v_sub_f32_e32 v104, v104, v105
	v_mul_f32_e32 v105, 0x3e16c740, v102
	v_mov_b32_e32 v102, v69
	v_mov_b32_e32 v103, v67
	v_pk_mul_f32 v[102:103], v[102:103], v[116:117] op_sel_hi:[1,0]
	v_mul_f32_e32 v104, 0x3e16c740, v104
	v_pk_mul_f32 v[100:101], v[100:101], v[102:103]
	s_nop 0
	v_pk_mul_f32 v[102:103], v[80:81], v[100:101]
	v_pk_mul_f32 v[100:101], v[80:81], v[100:101] op_sel:[1,0] op_sel_hi:[0,1]
	v_sub_f32_e32 v102, v102, v103
	v_add_f32_e32 v100, v100, v101
	v_mul_f32_e32 v102, 0x3e16c740, v102
	v_mul_f32_e32 v103, 0x3e16c740, v100
	v_cvt_pk_bf16_f32 v100, v7, v109
	v_cvt_pk_bf16_f32 v101, v104, v102
	global_store_dwordx2 v[98:99], v[100:101], off offset:320 nt
	v_cvt_pk_bf16_f32 v100, v108, v115
	v_cvt_pk_bf16_f32 v101, v105, v103
	global_store_dwordx2 v[98:99], v[100:101], off offset:352 nt

.Lew4_11:
	v_mul_f32_e32 v58, v85, v85
	v_fmac_f32_e32 v7, v88, v88
	v_fmac_f32_e32 v58, v84, v84
	v_add_f32_e32 v7, v7, v58
	v_mul_f32_e32 v58, v87, v87
	v_mul_f32_e32 v59, v83, v83
	v_fmac_f32_e32 v58, v86, v86
	v_fmac_f32_e32 v59, v82, v82
	v_add_f32_e32 v58, v58, v59
	v_add_f32_e32 v7, v7, v58
	v_mul_f32_e32 v58, v73, v73
	v_mul_f32_e32 v59, v69, v69
	v_fmac_f32_e32 v58, v72, v72
	v_fmac_f32_e32 v59, v68, v68
	v_add_f32_e32 v58, v58, v59
	v_mul_f32_e32 v59, v71, v71
	v_mul_f32_e32 v60, v67, v67
	v_fmac_f32_e32 v59, v70, v70
	v_fmac_f32_e32 v60, v66, v66
	v_add_f32_e32 v59, v59, v60
	v_add_f32_e32 v58, v58, v59
	v_add_f32_e32 v7, v7, v58
	v_mov_b32_e32 v58, v7
	s_nop 1
	v_permlane16_swap_b32_e32 v7, v58
	v_add_f32_e32 v7, v7, v58
	v_mov_b32_e32 v58, v7
	s_nop 1
	v_permlane32_swap_b32_e32 v7, v58
	v_add_f32_e32 v7, v7, v58
	v_fmamk_f32 v7, v7, 0x3c800000, v217
	v_rsq_f32_e32 v7, v7
	v_pk_mul_f32 v[58:59], v[38:39], v[88:89]
	v_pk_mul_f32 v[60:61], v[40:41], v[84:85]
	v_pk_mul_f32 v[64:65], v[36:37], v[82:83]
	v_mul_f32_e32 v7, 0x3e16c740, v7
	v_mul_f32_e32 v58, v58, v7
	v_mul_f32_e32 v59, v59, v7
	v_pk_mul_f32 v[82:83], v[34:35], v[86:87]
	v_cvt_pk_bf16_f32 v58, v58, v59
	v_mul_f32_e32 v59, v60, v7
	v_mul_f32_e32 v60, v61, v7
	v_cvt_pk_bf16_f32 v59, v59, v60
	v_mul_f32_e32 v60, v82, v7
	v_mul_f32_e32 v61, v83, v7
	v_mad_i64_i32 v[62:63], s[0:1], v114, s70, v[146:147]
	v_cvt_pk_bf16_f32 v60, v60, v61
	v_mul_f32_e32 v61, v64, v7
	v_mul_f32_e32 v64, v65, v7
	v_cvt_pk_bf16_f32 v61, v61, v64
	global_store_dwordx4 v[62:63], v[58:61], off nt
	v_pk_mul_f32 v[64:65], v[28:29], v[66:67]
	v_pk_mul_f32 v[66:67], v[26:27], v[70:71]
	v_pk_mul_f32 v[58:59], v[30:31], v[72:73]
	v_pk_mul_f32 v[60:61], v[32:33], v[68:69]
	v_mul_f32_e32 v58, v58, v7
	v_mul_f32_e32 v59, v59, v7
	v_cvt_pk_bf16_f32 v58, v58, v59
	v_mul_f32_e32 v59, v60, v7
	v_mul_f32_e32 v60, v61, v7
	v_cvt_pk_bf16_f32 v59, v59, v60
	v_mul_f32_e32 v60, v66, v7
	v_mul_f32_e32 v61, v67, v7
	v_cvt_pk_bf16_f32 v60, v60, v61
	v_mul_f32_e32 v61, v64, v7
	v_mul_f32_e32 v7, v65, v7
	v_cvt_pk_bf16_f32 v61, v61, v7
	global_store_dwordx4 v[62:63], v[58:61], off offset:64 nt
	v_mov_b64_e32 v[62:63], v[78:79]
	v_mov_b64_e32 v[64:65], v[80:81]
	v_mov_b64_e32 v[58:59], v[74:75]
	v_mov_b64_e32 v[60:61], v[76:77]

.Lew4_12:
	v_add_f32_e32 v7, v94, v95
	v_add_f32_e32 v66, v96, v97
	v_add_f32_e32 v7, v7, v66
	v_fmaak_f32 v7, v3, v7, 0x358637bd
	v_rsq_f32_e32 v74, v7
	s_and_b64 vcc, exec, s[8:9]
	s_mov_b64 s[50:51], -1
	v_pk_mul_f32 v[68:69], v[56:57], v[74:75] op_sel_hi:[1,0]
	v_pk_mul_f32 v[72:73], v[54:55], v[74:75] op_sel_hi:[1,0]
	v_pk_mul_f32 v[66:67], v[52:53], v[74:75] op_sel_hi:[1,0]
	v_pk_mul_f32 v[70:71], v[50:51], v[74:75] op_sel_hi:[1,0]
	v_pk_mul_f32 v[52:53], v[48:49], v[74:75] op_sel_hi:[1,0]
	v_pk_mul_f32 v[56:57], v[46:47], v[74:75] op_sel_hi:[1,0]
	v_pk_mul_f32 v[50:51], v[44:45], v[74:75] op_sel_hi:[1,0]
	v_pk_mul_f32 v[54:55], v[42:43], v[74:75] op_sel_hi:[1,0]
	s_cbranch_vccnz .LBB0_1135
	s_and_b64 vcc, exec, s[6:7]
	s_cbranch_vccnz .LBB0_1132
	v_lshlrev_b64 v[42:43], 11, v[112:113]
	v_lshl_add_u64 v[42:43], v[4:5], 0, v[42:43]
	s_andn2_b64 vcc, exec, s[26:27]
	s_cbranch_vccnz .LBB0_1129
	v_cvt_pk_bf16_f32 v44, v72, v73
	v_cvt_pk_bf16_f32 v45, v68, v69
	v_cvt_pk_bf16_f32 v46, v70, v71
	v_cvt_pk_bf16_f32 v47, v66, v67
	s_mov_b64 s[50:51], 0
	global_store_dwordx4 v[42:43], v[44:47], off nt
	s_nop 1
	v_cvt_pk_bf16_f32 v44, v56, v57
	v_cvt_pk_bf16_f32 v45, v52, v53
	v_cvt_pk_bf16_f32 v46, v54, v55
	v_cvt_pk_bf16_f32 v47, v50, v51
	global_store_dwordx4 v[42:43], v[44:47], off offset:64 nt
.LBB0_1129:
	s_andn2_b64 vcc, exec, s[50:51]
	s_cbranch_vccnz .LBB0_1131
	v_mul_f32_e32 v7, v73, v73
	v_mul_f32_e32 v44, v69, v69
	v_fmac_f32_e32 v7, v72, v72
	v_fmac_f32_e32 v44, v68, v68
	v_add_f32_e32 v7, v7, v44
	v_mul_f32_e32 v44, v71, v71
	v_mul_f32_e32 v45, v67, v67
	v_fmac_f32_e32 v44, v70, v70
	v_fmac_f32_e32 v45, v66, v66
	v_add_f32_e32 v44, v44, v45
	v_add_f32_e32 v7, v7, v44
	v_mul_f32_e32 v44, v57, v57
	v_mul_f32_e32 v45, v53, v53
	v_fmac_f32_e32 v44, v56, v56
	v_fmac_f32_e32 v45, v52, v52
	v_add_f32_e32 v44, v44, v45
	v_mul_f32_e32 v45, v55, v55
	v_mul_f32_e32 v46, v51, v51
	v_fmac_f32_e32 v45, v54, v54
	v_fmac_f32_e32 v46, v50, v50
	v_add_f32_e32 v45, v45, v46
	v_add_f32_e32 v44, v44, v45
	v_add_f32_e32 v7, v7, v44
	v_mov_b32_e32 v44, v7
	s_nop 1
	v_permlane16_swap_b32_e32 v7, v44
	v_add_f32_e32 v7, v7, v44
	v_mov_b32_e32 v44, v7
	s_nop 1
	v_permlane32_swap_b32_e32 v7, v44
	v_add_f32_e32 v7, v7, v44
	v_fmamk_f32 v7, v7, 0x3c800000, v217
	v_rsq_f32_e32 v7, v7
	v_pk_mul_f32 v[44:45], v[38:39], v[72:73]
	v_pk_mul_f32 v[46:47], v[40:41], v[68:69]
	v_pk_mul_f32 v[74:75], v[34:35], v[70:71]
	v_mul_f32_e32 v44, v44, v7
	v_mul_f32_e32 v45, v45, v7
	v_cvt_pk_bf16_f32 v44, v44, v45
	v_mul_f32_e32 v45, v46, v7
	v_mul_f32_e32 v46, v47, v7
	v_pk_mul_f32 v[48:49], v[36:37], v[66:67]
	v_cvt_pk_bf16_f32 v45, v45, v46
	v_mul_f32_e32 v46, v74, v7
	v_mul_f32_e32 v47, v75, v7
	v_cvt_pk_bf16_f32 v46, v46, v47
	v_mul_f32_e32 v47, v48, v7
	v_mul_f32_e32 v48, v49, v7
	v_cvt_pk_bf16_f32 v47, v47, v48
	global_store_dwordx4 v[42:43], v[44:47], off nt
	v_pk_mul_f32 v[74:75], v[26:27], v[54:55]
	v_pk_mul_f32 v[48:49], v[28:29], v[50:51]
	v_pk_mul_f32 v[44:45], v[30:31], v[56:57]
	v_pk_mul_f32 v[46:47], v[32:33], v[52:53]
	v_mul_f32_e32 v44, v44, v7
	v_mul_f32_e32 v45, v45, v7
	v_cvt_pk_bf16_f32 v44, v44, v45
	v_mul_f32_e32 v45, v46, v7
	v_mul_f32_e32 v46, v47, v7
	v_cvt_pk_bf16_f32 v45, v45, v46
	v_mul_f32_e32 v46, v74, v7
	v_mul_f32_e32 v47, v75, v7
	v_cvt_pk_bf16_f32 v46, v46, v47
	v_mul_f32_e32 v47, v48, v7
	v_mul_f32_e32 v7, v49, v7
	v_cvt_pk_bf16_f32 v47, v47, v7
	global_store_dwordx4 v[42:43], v[44:47], off offset:64 nt

.LBB0_1132:
	s_nop 0
	v_mov_b64_e32 v[46:47], v[58:59]
	v_mov_b64_e32 v[42:43], v[62:63]
	s_andn2_b64 vcc, exec, s[50:51]
	v_mov_b64_e32 v[48:49], v[60:61]
	v_mov_b64_e32 v[44:45], v[64:65]
	s_cbranch_vccnz .LBB0_1134
	v_ashrrev_i32_e32 v7, 31, v110
	v_lshrrev_b32_e32 v7, 19, v7
	v_add_u32_e32 v7, v110, v7
	v_and_b32_e32 v7, 0xffffe000, v7
	v_sub_u32_e32 v42, v110, v7
	v_ashrrev_i32_e32 v43, 31, v42
	v_lshlrev_b64 v[42:43], 7, v[42:43]
	v_lshl_add_u64 v[46:47], v[198:199], 0, v[42:43]
	global_load_dwordx4 v[42:45], v[46:47], off offset:16
	s_nop 0
	global_load_dwordx4 v[46:49], v[46:47], off
	v_mul_f32_e32 v7, v73, v73
	v_mul_f32_e32 v74, v69, v69
	v_fmac_f32_e32 v7, v72, v72
	v_fmac_f32_e32 v74, v68, v68
	v_add_f32_e32 v7, v7, v74
	v_mul_f32_e32 v74, v71, v71
	v_mul_f32_e32 v75, v67, v67
	v_fmac_f32_e32 v74, v70, v70
	v_fmac_f32_e32 v75, v66, v66
	v_add_f32_e32 v74, v74, v75
	v_add_f32_e32 v7, v7, v74
	v_mov_b32_e32 v74, v7
	s_nop 1
	v_permlane16_swap_b32_e32 v7, v74
	v_add_f32_e32 v7, v7, v74
	v_mov_b32_e32 v74, v7
	s_nop 1
	v_permlane32_swap_b32_e32 v7, v74
	v_add_f32_e32 v7, v7, v74
	v_fmamk_f32 v7, v7, 0x3d000000, v217
	v_rsq_f32_e32 v74, v7
	v_mov_b32_e32 v76, v72
	v_mov_b32_e32 v77, v70
	v_mov_b32_e32 v78, v38
	v_pk_mul_f32 v[76:77], v[76:77], v[74:75] op_sel_hi:[1,0]
	v_mov_b32_e32 v79, v34
	v_pk_mul_f32 v[76:77], v[78:79], v[76:77]
	s_nop 0
	v_pk_mul_f32 v[80:81], v[58:59], v[76:77]
	v_pk_mul_f32 v[76:77], v[58:59], v[76:77] op_sel:[1,0] op_sel_hi:[0,1]
	v_add_f32_e32 v75, v76, v77
	v_mov_b32_e32 v76, v73
	v_mov_b32_e32 v77, v71
	v_sub_f32_e32 v7, v80, v81
	v_pk_mul_f32 v[76:77], v[76:77], v[74:75] op_sel_hi:[1,0]
	v_mov_b32_e32 v80, v39
	v_mov_b32_e32 v81, v35
	v_pk_mul_f32 v[76:77], v[80:81], v[76:77]
	v_mul_f32_e32 v86, 0x3e16c740, v75
	v_pk_mul_f32 v[82:83], v[60:61], v[76:77]
	v_pk_mul_f32 v[76:77], v[60:61], v[76:77] op_sel:[1,0] op_sel_hi:[0,1]
	v_sub_f32_e32 v75, v82, v83
	v_mul_f32_e32 v87, 0x3e16c740, v75
	v_add_f32_e32 v75, v76, v77
	v_mov_b32_e32 v76, v68
	v_mov_b32_e32 v77, v66
	v_pk_mul_f32 v[76:77], v[76:77], v[74:75] op_sel_hi:[1,0]
	v_mov_b32_e32 v82, v40
	v_mov_b32_e32 v83, v36
	v_pk_mul_f32 v[76:77], v[82:83], v[76:77]
	v_mul_f32_e32 v88, 0x3e16c740, v75
	v_pk_mul_f32 v[84:85], v[62:63], v[76:77]
	v_pk_mul_f32 v[76:77], v[62:63], v[76:77] op_sel:[1,0] op_sel_hi:[0,1]
	v_sub_f32_e32 v75, v84, v85
	v_mul_f32_e32 v89, 0x3e16c740, v75
	v_add_f32_e32 v75, v76, v77
	v_mov_b32_e32 v76, v69
	v_mov_b32_e32 v77, v67
	v_mul_f32_e32 v94, 0x3e16c740, v75
	v_pk_mul_f32 v[74:75], v[76:77], v[74:75] op_sel_hi:[1,0]
	v_mov_b32_e32 v76, v41
	v_mov_b32_e32 v77, v37
	v_pk_mul_f32 v[74:75], v[76:77], v[74:75]
	v_mul_f32_e32 v7, 0x3e16c740, v7
	v_pk_mul_f32 v[84:85], v[64:65], v[74:75]
	v_pk_mul_f32 v[74:75], v[64:65], v[74:75] op_sel:[1,0] op_sel_hi:[0,1]
	v_add_f32_e32 v74, v74, v75
	v_mul_f32_e32 v95, 0x3e16c740, v74
	v_mov_b64_e32 v[74:75], s[28:29]
	v_sub_f32_e32 v84, v84, v85
	v_mad_i64_i32 v[74:75], s[0:1], v112, s70, v[74:75]
	v_mul_f32_e32 v85, 0x3e16c740, v84
	v_cvt_pk_bf16_f32 v84, v7, v87
	v_lshl_add_u64 v[74:75], v[8:9], 1, v[74:75]
	v_cvt_pk_bf16_f32 v85, v89, v85
	global_store_dwordx2 v[74:75], v[84:85], off offset:128 nt
	v_cvt_pk_bf16_f32 v84, v86, v88
	v_mul_f32_e32 v7, v57, v57
	v_mul_f32_e32 v86, v53, v53
	v_fmac_f32_e32 v7, v56, v56
	v_fmac_f32_e32 v86, v52, v52
	v_add_f32_e32 v7, v7, v86
	v_mul_f32_e32 v86, v55, v55
	v_mul_f32_e32 v87, v51, v51
	v_fmac_f32_e32 v86, v54, v54
	v_fmac_f32_e32 v87, v50, v50
	v_add_f32_e32 v86, v86, v87
	v_add_f32_e32 v7, v7, v86
	v_mov_b32_e32 v86, v7
	s_nop 1
	v_permlane16_swap_b32_e32 v7, v86
	v_add_f32_e32 v7, v7, v86
	v_mov_b32_e32 v86, v7
	s_nop 1
	v_permlane32_swap_b32_e32 v7, v86
	v_add_f32_e32 v7, v7, v86
	v_fmamk_f32 v7, v7, 0x3d000000, v217
	v_rsq_f32_e32 v86, v7
	v_cvt_pk_bf16_f32 v85, v94, v95
	global_store_dwordx2 v[74:75], v[84:85], off offset:160 nt
	v_mov_b32_e32 v84, v56
	v_mov_b32_e32 v85, v54
	v_pk_mul_f32 v[84:85], v[84:85], v[86:87] op_sel_hi:[1,0]
	s_nop 0
	v_pk_mul_f32 v[78:79], v[78:79], v[84:85]
	s_nop 0
	v_pk_mul_f32 v[84:85], v[58:59], v[78:79]
	v_pk_mul_f32 v[78:79], v[58:59], v[78:79] op_sel:[1,0] op_sel_hi:[0,1]
	v_add_f32_e32 v78, v78, v79
	v_sub_f32_e32 v7, v84, v85
	v_mul_f32_e32 v84, 0x3e16c740, v78
	v_mov_b32_e32 v78, v57
	v_mov_b32_e32 v79, v55
	v_pk_mul_f32 v[78:79], v[78:79], v[86:87] op_sel_hi:[1,0]
	v_mul_f32_e32 v7, 0x3e16c740, v7
	v_pk_mul_f32 v[78:79], v[80:81], v[78:79]
	s_nop 0
	v_pk_mul_f32 v[80:81], v[60:61], v[78:79]
	v_pk_mul_f32 v[78:79], v[60:61], v[78:79] op_sel:[1,0] op_sel_hi:[0,1]
	v_add_f32_e32 v78, v78, v79
	v_mul_f32_e32 v87, 0x3e16c740, v78
	v_mov_b32_e32 v78, v52
	v_mov_b32_e32 v79, v50
	v_pk_mul_f32 v[78:79], v[78:79], v[86:87] op_sel_hi:[1,0]
	v_sub_f32_e32 v80, v80, v81
	v_pk_mul_f32 v[78:79], v[82:83], v[78:79]
	v_mul_f32_e32 v85, 0x3e16c740, v80
	v_pk_mul_f32 v[80:81], v[62:63], v[78:79]
	v_pk_mul_f32 v[78:79], v[62:63], v[78:79] op_sel:[1,0] op_sel_hi:[0,1]
	v_add_f32_e32 v78, v78, v79
	v_sub_f32_e32 v80, v80, v81
	v_mul_f32_e32 v81, 0x3e16c740, v78
	v_mov_b32_e32 v78, v53
	v_mov_b32_e32 v79, v51
	v_pk_mul_f32 v[78:79], v[78:79], v[86:87] op_sel_hi:[1,0]
	v_mul_f32_e32 v80, 0x3e16c740, v80
	v_pk_mul_f32 v[76:77], v[76:77], v[78:79]
	s_nop 0
	v_pk_mul_f32 v[78:79], v[64:65], v[76:77]
	v_pk_mul_f32 v[76:77], v[64:65], v[76:77] op_sel:[1,0] op_sel_hi:[0,1]
	v_sub_f32_e32 v78, v78, v79
	v_add_f32_e32 v76, v76, v77
	v_mul_f32_e32 v78, 0x3e16c740, v78
	v_mul_f32_e32 v79, 0x3e16c740, v76
	v_cvt_pk_bf16_f32 v76, v7, v85
	v_cvt_pk_bf16_f32 v77, v80, v78
	global_store_dwordx2 v[74:75], v[76:77], off offset:320 nt
	v_cvt_pk_bf16_f32 v76, v84, v87
	v_cvt_pk_bf16_f32 v77, v81, v79
	global_store_dwordx2 v[74:75], v[76:77], off offset:352 nt

.Lew4_14:
	v_pk_mul_f32 v[48:49], v[36:37], v[66:67]
	v_mul_f32_e32 v7, 0x3e16c740, v7
	v_mul_f32_e32 v42, v42, v7
	v_mul_f32_e32 v43, v43, v7
	v_pk_mul_f32 v[66:67], v[34:35], v[70:71]
	v_cvt_pk_bf16_f32 v42, v42, v43
	v_mul_f32_e32 v43, v44, v7
	v_mul_f32_e32 v44, v45, v7
	v_cvt_pk_bf16_f32 v43, v43, v44
	v_mul_f32_e32 v44, v66, v7
	v_mul_f32_e32 v45, v67, v7
	v_mad_i64_i32 v[46:47], s[0:1], v112, s70, v[146:147]
	v_cvt_pk_bf16_f32 v44, v44, v45
	v_mul_f32_e32 v45, v48, v7
	v_mul_f32_e32 v48, v49, v7
	v_cvt_pk_bf16_f32 v45, v45, v48
	global_store_dwordx4 v[46:47], v[42:45], off nt
	v_pk_mul_f32 v[48:49], v[28:29], v[50:51]
	v_pk_mul_f32 v[50:51], v[26:27], v[54:55]
	v_pk_mul_f32 v[42:43], v[30:31], v[56:57]
	v_pk_mul_f32 v[44:45], v[32:33], v[52:53]
	v_mul_f32_e32 v42, v42, v7
	v_mul_f32_e32 v43, v43, v7
	v_cvt_pk_bf16_f32 v42, v42, v43
	v_mul_f32_e32 v43, v44, v7
	v_mul_f32_e32 v44, v45, v7
	v_cvt_pk_bf16_f32 v43, v43, v44
	v_mul_f32_e32 v44, v50, v7
	v_mul_f32_e32 v45, v51, v7
	v_cvt_pk_bf16_f32 v44, v44, v45
	v_mul_f32_e32 v45, v48, v7
	v_mul_f32_e32 v7, v49, v7
	v_cvt_pk_bf16_f32 v45, v45, v7
	global_store_dwordx4 v[46:47], v[42:45], off offset:64 nt
	v_mov_b64_e32 v[46:47], v[58:59]
	v_mov_b64_e32 v[48:49], v[60:61]
	v_mov_b64_e32 v[42:43], v[62:63]
	v_mov_b64_e32 v[44:45], v[64:65]

.LBB0_1140:
	s_and_b64 vcc, exec, s[6:7]
	s_mov_b64 s[6:7], -1
	s_cbranch_vccnz .LBB0_1146
	v_lshlrev_b64 v[50:51], 11, v[110:111]
	v_lshl_add_u64 v[4:5], v[4:5], 0, v[50:51]
	s_andn2_b64 vcc, exec, s[26:27]
	s_cbranch_vccnz .LBB0_1143
	v_cvt_pk_bf16_f32 v50, v22, v23
	v_cvt_pk_bf16_f32 v51, v24, v25
	v_cvt_pk_bf16_f32 v52, v18, v19
	v_cvt_pk_bf16_f32 v53, v20, v21
	s_mov_b64 s[6:7], 0
	global_store_dwordx4 v[4:5], v[50:53], off nt
	s_nop 1
	v_cvt_pk_bf16_f32 v50, v14, v15
	v_cvt_pk_bf16_f32 v51, v16, v17
	v_cvt_pk_bf16_f32 v52, v10, v11
	v_cvt_pk_bf16_f32 v53, v12, v13
	global_store_dwordx4 v[4:5], v[50:53], off offset:64 nt
.LBB0_1143:
	s_andn2_b64 vcc, exec, s[6:7]
	s_cbranch_vccnz .LBB0_1145
	v_mul_f32_e32 v3, v23, v23
	v_mul_f32_e32 v7, v25, v25
	v_fmac_f32_e32 v3, v22, v22
	v_fmac_f32_e32 v7, v24, v24
	v_add_f32_e32 v3, v3, v7
	v_mul_f32_e32 v7, v19, v19
	v_mul_f32_e32 v50, v21, v21
	v_fmac_f32_e32 v7, v18, v18
	v_fmac_f32_e32 v50, v20, v20
	v_add_f32_e32 v7, v7, v50
	v_add_f32_e32 v3, v3, v7
	v_mul_f32_e32 v7, v15, v15
	v_mul_f32_e32 v50, v17, v17
	v_fmac_f32_e32 v7, v14, v14
	v_fmac_f32_e32 v50, v16, v16
	v_add_f32_e32 v7, v7, v50
	v_mul_f32_e32 v50, v11, v11
	v_mul_f32_e32 v51, v13, v13
	v_fmac_f32_e32 v50, v10, v10
	v_fmac_f32_e32 v51, v12, v12
	v_add_f32_e32 v50, v50, v51
	v_add_f32_e32 v7, v7, v50
	v_add_f32_e32 v3, v3, v7
	v_mov_b32_e32 v7, v3
	s_nop 1
	v_permlane16_swap_b32_e32 v3, v7
	v_add_f32_e32 v3, v3, v7
	v_mov_b32_e32 v7, v3
	s_nop 1
	v_permlane32_swap_b32_e32 v3, v7
	v_add_f32_e32 v3, v3, v7
	v_fmamk_f32 v3, v3, 0x3c800000, v217
	v_rsq_f32_e32 v3, v3
	v_pk_mul_f32 v[50:51], v[38:39], v[22:23]
	v_pk_mul_f32 v[52:53], v[40:41], v[24:25]
	v_pk_mul_f32 v[54:55], v[36:37], v[20:21]
	v_mul_f32_e32 v7, v50, v3
	v_mul_f32_e32 v50, v51, v3
	v_pk_mul_f32 v[56:57], v[34:35], v[18:19]
	v_cvt_pk_bf16_f32 v50, v7, v50
	v_mul_f32_e32 v7, v52, v3
	v_mul_f32_e32 v51, v53, v3
	v_cvt_pk_bf16_f32 v51, v7, v51
	v_mul_f32_e32 v7, v56, v3
	v_mul_f32_e32 v52, v57, v3
	v_mul_f32_e32 v53, v55, v3
	v_cvt_pk_bf16_f32 v52, v7, v52
	v_mul_f32_e32 v7, v54, v3
	v_cvt_pk_bf16_f32 v53, v7, v53
	global_store_dwordx4 v[4:5], v[50:53], off nt
	v_pk_mul_f32 v[56:57], v[26:27], v[10:11]
	v_pk_mul_f32 v[54:55], v[28:29], v[12:13]
	v_pk_mul_f32 v[50:51], v[30:31], v[14:15]
	v_pk_mul_f32 v[52:53], v[32:33], v[16:17]
	v_mul_f32_e32 v7, v50, v3
	v_mul_f32_e32 v50, v51, v3
	v_cvt_pk_bf16_f32 v50, v7, v50
	v_mul_f32_e32 v7, v52, v3
	v_mul_f32_e32 v51, v53, v3
	v_cvt_pk_bf16_f32 v51, v7, v51
	v_mul_f32_e32 v7, v56, v3
	v_mul_f32_e32 v52, v57, v3
	v_cvt_pk_bf16_f32 v52, v7, v52
	v_mul_f32_e32 v7, v54, v3
	v_mul_f32_e32 v3, v55, v3
	v_cvt_pk_bf16_f32 v53, v7, v3
	global_store_dwordx4 v[4:5], v[50:53], off offset:64 nt

.LBB0_1146:
	s_andn2_b64 vcc, exec, s[6:7]
	s_cbranch_vccnz .LBB0_1148
	v_mul_f32_e32 v3, v23, v23
	v_mul_f32_e32 v4, v25, v25
	v_fmac_f32_e32 v3, v22, v22
	v_fmac_f32_e32 v4, v24, v24
	v_add_f32_e32 v3, v3, v4
	v_mul_f32_e32 v4, v19, v19
	v_mul_f32_e32 v5, v21, v21
	v_fmac_f32_e32 v4, v18, v18
	v_fmac_f32_e32 v5, v20, v20
	v_add_f32_e32 v4, v4, v5
	v_add_f32_e32 v3, v3, v4
	v_mov_b32_e32 v4, v3
	s_nop 1
	v_permlane16_swap_b32_e32 v3, v4
	v_add_f32_e32 v3, v3, v4
	v_mov_b32_e32 v4, v3
	s_nop 1
	v_permlane32_swap_b32_e32 v3, v4
	v_add_f32_e32 v3, v3, v4
	v_fmamk_f32 v3, v3, 0x3d000000, v217
	v_rsq_f32_e32 v4, v3
	v_mov_b32_e32 v50, v22
	v_mov_b32_e32 v51, v18
	v_mov_b32_e32 v52, v38
	v_pk_mul_f32 v[50:51], v[50:51], v[4:5] op_sel_hi:[1,0]
	v_mov_b32_e32 v53, v34
	v_pk_mul_f32 v[50:51], v[52:53], v[50:51]
	s_nop 0
	v_pk_mul_f32 v[54:55], v[46:47], v[50:51]
	v_pk_mul_f32 v[50:51], v[46:47], v[50:51] op_sel:[1,0] op_sel_hi:[0,1]
	v_add_f32_e32 v5, v50, v51
	v_mov_b32_e32 v50, v23
	v_mov_b32_e32 v51, v19
	v_sub_f32_e32 v3, v54, v55
	v_pk_mul_f32 v[50:51], v[50:51], v[4:5] op_sel_hi:[1,0]
	v_mov_b32_e32 v54, v39
	v_mov_b32_e32 v55, v35
	v_pk_mul_f32 v[50:51], v[54:55], v[50:51]
	v_mul_f32_e32 v7, 0x3e16c740, v5
	v_pk_mul_f32 v[56:57], v[48:49], v[50:51]
	v_pk_mul_f32 v[50:51], v[48:49], v[50:51] op_sel:[1,0] op_sel_hi:[0,1]
	v_sub_f32_e32 v5, v56, v57
	v_mul_f32_e32 v60, 0x3e16c740, v5
	v_add_f32_e32 v5, v50, v51
	v_mov_b32_e32 v50, v24
	v_mov_b32_e32 v51, v20
	v_pk_mul_f32 v[50:51], v[50:51], v[4:5] op_sel_hi:[1,0]
	v_mov_b32_e32 v56, v40
	v_mov_b32_e32 v57, v36
	v_pk_mul_f32 v[50:51], v[56:57], v[50:51]
	v_mul_f32_e32 v61, 0x3e16c740, v5
	v_pk_mul_f32 v[58:59], v[42:43], v[50:51]
	v_pk_mul_f32 v[50:51], v[42:43], v[50:51] op_sel:[1,0] op_sel_hi:[0,1]
	v_sub_f32_e32 v5, v58, v59
	v_mul_f32_e32 v62, 0x3e16c740, v5
	v_add_f32_e32 v5, v50, v51
	v_mov_b32_e32 v50, v25
	v_mov_b32_e32 v51, v21
	v_mul_f32_e32 v63, 0x3e16c740, v5
	v_pk_mul_f32 v[4:5], v[50:51], v[4:5] op_sel_hi:[1,0]
	v_mov_b32_e32 v50, v41
	v_mov_b32_e32 v51, v37
	v_pk_mul_f32 v[4:5], v[50:51], v[4:5]
	v_mul_f32_e32 v3, 0x3e16c740, v3
	v_pk_mul_f32 v[58:59], v[44:45], v[4:5]
	v_pk_mul_f32 v[4:5], v[44:45], v[4:5] op_sel:[1,0] op_sel_hi:[0,1]
	v_add_f32_e32 v4, v4, v5
	v_mul_f32_e32 v64, 0x3e16c740, v4
	v_mov_b64_e32 v[4:5], s[28:29]
	v_sub_f32_e32 v58, v58, v59
	v_mad_i64_i32 v[4:5], s[0:1], v110, s70, v[4:5]
	v_mul_f32_e32 v59, 0x3e16c740, v58
	v_lshl_add_u64 v[4:5], v[8:9], 1, v[4:5]
	v_cvt_pk_bf16_f32 v58, v3, v60
	v_cvt_pk_bf16_f32 v59, v62, v59
	global_store_dwordx2 v[4:5], v[58:59], off offset:128 nt
	v_cvt_pk_bf16_f32 v8, v7, v61
	v_mul_f32_e32 v3, v15, v15
	v_mul_f32_e32 v7, v17, v17
	v_fmac_f32_e32 v3, v14, v14
	v_fmac_f32_e32 v7, v16, v16
	v_add_f32_e32 v3, v3, v7
	v_mul_f32_e32 v7, v11, v11
	v_mul_f32_e32 v58, v13, v13
	v_fmac_f32_e32 v7, v10, v10
	v_fmac_f32_e32 v58, v12, v12
	v_add_f32_e32 v7, v7, v58
	v_add_f32_e32 v3, v3, v7
	v_mov_b32_e32 v7, v3
	s_nop 1
	v_permlane16_swap_b32_e32 v3, v7
	v_add_f32_e32 v3, v3, v7
	v_mov_b32_e32 v7, v3
	s_nop 1
	v_permlane32_swap_b32_e32 v3, v7
	v_add_f32_e32 v3, v3, v7
	v_fmamk_f32 v3, v3, 0x3d000000, v217
	v_rsq_f32_e32 v58, v3
	v_cvt_pk_bf16_f32 v9, v63, v64
	global_store_dwordx2 v[4:5], v[8:9], off offset:160 nt
	v_mov_b32_e32 v8, v14
	v_mov_b32_e32 v9, v10
	v_pk_mul_f32 v[8:9], v[8:9], v[58:59] op_sel_hi:[1,0]
	s_nop 0
	v_pk_mul_f32 v[8:9], v[52:53], v[8:9]
	s_nop 0
	v_pk_mul_f32 v[52:53], v[46:47], v[8:9]
	v_pk_mul_f32 v[8:9], v[46:47], v[8:9] op_sel:[1,0] op_sel_hi:[0,1]
	v_add_f32_e32 v7, v8, v9
	v_mov_b32_e32 v8, v15
	v_mov_b32_e32 v9, v11
	v_pk_mul_f32 v[8:9], v[8:9], v[58:59] op_sel_hi:[1,0]
	v_sub_f32_e32 v3, v52, v53
	v_pk_mul_f32 v[8:9], v[54:55], v[8:9]
	v_mul_f32_e32 v3, 0x3e16c740, v3
	v_pk_mul_f32 v[46:47], v[48:49], v[8:9]
	v_pk_mul_f32 v[8:9], v[48:49], v[8:9] op_sel:[1,0] op_sel_hi:[0,1]
	v_add_f32_e32 v8, v8, v9
	v_mul_f32_e32 v48, 0x3e16c740, v8
	v_mov_b32_e32 v8, v16
	v_mov_b32_e32 v9, v12
	v_pk_mul_f32 v[8:9], v[8:9], v[58:59] op_sel_hi:[1,0]
	v_sub_f32_e32 v46, v46, v47
	v_pk_mul_f32 v[8:9], v[56:57], v[8:9]
	v_mul_f32_e32 v52, 0x3e16c740, v46
	v_pk_mul_f32 v[46:47], v[42:43], v[8:9]
	v_pk_mul_f32 v[8:9], v[42:43], v[8:9] op_sel:[1,0] op_sel_hi:[0,1]
	v_add_f32_e32 v8, v8, v9
	v_sub_f32_e32 v46, v46, v47
	v_mul_f32_e32 v47, 0x3e16c740, v8
	v_mov_b32_e32 v8, v17
	v_mov_b32_e32 v9, v13
	v_pk_mul_f32 v[8:9], v[8:9], v[58:59] op_sel_hi:[1,0]
	v_mul_f32_e32 v46, 0x3e16c740, v46
	v_pk_mul_f32 v[8:9], v[50:51], v[8:9]
	v_mul_f32_e32 v7, 0x3e16c740, v7
	v_pk_mul_f32 v[42:43], v[44:45], v[8:9]
	v_pk_mul_f32 v[8:9], v[44:45], v[8:9] op_sel:[1,0] op_sel_hi:[0,1]
	v_sub_f32_e32 v42, v42, v43
	v_add_f32_e32 v8, v8, v9
	v_mul_f32_e32 v42, 0x3e16c740, v42
	v_mul_f32_e32 v43, 0x3e16c740, v8
	v_cvt_pk_bf16_f32 v8, v3, v52
	v_cvt_pk_bf16_f32 v9, v46, v42
	global_store_dwordx2 v[4:5], v[8:9], off offset:320 nt
	v_cvt_pk_bf16_f32 v8, v7, v48
	v_cvt_pk_bf16_f32 v9, v47, v43
	global_store_dwordx2 v[4:5], v[8:9], off offset:352 nt

.LBB0_1149:
	v_mul_f32_e32 v3, v23, v23
	v_mul_f32_e32 v4, v25, v25
	v_fmac_f32_e32 v3, v22, v22
	v_fmac_f32_e32 v4, v24, v24
	v_add_f32_e32 v3, v3, v4
	v_mul_f32_e32 v4, v19, v19
	v_mul_f32_e32 v5, v21, v21
	v_fmac_f32_e32 v4, v18, v18
	v_fmac_f32_e32 v5, v20, v20
	v_add_f32_e32 v4, v4, v5
	v_add_f32_e32 v3, v3, v4
	v_mul_f32_e32 v4, v15, v15
	v_mul_f32_e32 v5, v17, v17
	v_fmac_f32_e32 v4, v14, v14
	v_fmac_f32_e32 v5, v16, v16
	v_add_f32_e32 v4, v4, v5
	v_mul_f32_e32 v5, v11, v11
	v_mul_f32_e32 v7, v13, v13
	v_fmac_f32_e32 v5, v10, v10
	v_fmac_f32_e32 v7, v12, v12
	v_add_f32_e32 v5, v5, v7
	v_add_f32_e32 v4, v4, v5
	v_add_f32_e32 v3, v3, v4
	v_mov_b32_e32 v4, v3
	s_nop 1
	v_permlane16_swap_b32_e32 v3, v4
	v_add_f32_e32 v3, v3, v4
	v_mov_b32_e32 v4, v3
	s_nop 1
	v_permlane32_swap_b32_e32 v3, v4
	v_add_f32_e32 v3, v3, v4
	v_fmamk_f32 v3, v3, 0x3c800000, v217
	v_rsq_f32_e32 v3, v3
	v_pk_mul_f32 v[22:23], v[38:39], v[22:23]
	v_pk_mul_f32 v[8:9], v[40:41], v[24:25]
	v_pk_mul_f32 v[24:25], v[36:37], v[20:21]
	v_mul_f32_e32 v3, 0x3e16c740, v3
	v_pk_mul_f32 v[20:21], v[34:35], v[18:19]
	v_mul_f32_e32 v7, v22, v3
	v_mul_f32_e32 v18, v23, v3
	v_cvt_pk_bf16_f32 v18, v7, v18
	v_mul_f32_e32 v7, v8, v3
	v_mul_f32_e32 v8, v9, v3
	v_cvt_pk_bf16_f32 v19, v7, v8
	v_mul_f32_e32 v8, v21, v3
	v_mul_f32_e32 v7, v20, v3
	v_cvt_pk_bf16_f32 v20, v7, v8
	v_mul_f32_e32 v8, v25, v3
	v_mul_f32_e32 v7, v24, v3
	v_cvt_pk_bf16_f32 v21, v7, v8
	v_pk_mul_f32 v[8:9], v[30:31], v[14:15]
	v_mad_i64_i32 v[4:5], s[0:1], v110, s70, v[146:147]
	v_pk_mul_f32 v[16:17], v[32:33], v[16:17]
	v_mul_f32_e32 v7, v8, v3
	v_mul_f32_e32 v8, v9, v3
	global_store_dwordx4 v[4:5], v[18:21], off nt
	v_pk_mul_f32 v[10:11], v[26:27], v[10:11]
	v_cvt_pk_bf16_f32 v8, v7, v8
	v_mul_f32_e32 v7, v16, v3
	v_mul_f32_e32 v9, v17, v3
	v_pk_mul_f32 v[12:13], v[28:29], v[12:13]
	v_cvt_pk_bf16_f32 v9, v7, v9
	v_mul_f32_e32 v7, v10, v3
	v_mul_f32_e32 v10, v11, v3
	v_cvt_pk_bf16_f32 v10, v7, v10
	v_mul_f32_e32 v7, v12, v3
	v_mul_f32_e32 v3, v13, v3
	v_cvt_pk_bf16_f32 v11, v7, v3
	global_store_dwordx4 v[4:5], v[8:11], off offset:64 nt
	s_and_b64 vcc, exec, s[4:5]
	s_mov_b64 s[4:5], -1
	s_cbranch_vccnz .LBB0_1032
